# v13: v7 + merged s_waitcnt vmcnt(8) lgkmcnt(0) before K-loop barriers
# speedup vs baseline: 1.0051x; 1.0036x over previous
.LBB0_271:
	s_add_u32 s26, s14, 0xfffc0080
	s_addc_u32 s27, s15, -1
	s_add_i32 s54, 0, 0x10000
	s_cmp_eq_u32 s53, 12
	s_cselect_b32 s29, s21, s27
	s_cselect_b32 s28, s49, s26
	v_add_u32_e32 v154, s54, v141
	s_cselect_b32 s27, s19, s52
	s_cselect_b32 s26, s50, s51
	s_add_i32 s56, 0, 0x14000
	ds_read_b128 v[146:149], v154
	ds_read_b128 v[150:153], v154 offset:1024
	ds_read_b128 v[162:165], v154 offset:2048
	ds_read_b128 v[166:169], v154 offset:3072
	v_add_u32_e32 v154, s56, v141
	ds_read_b128 v[170:173], v154
	ds_read_b128 v[186:189], v154 offset:1024
	ds_read_b128 v[190:193], v154 offset:2048
	ds_read_b128 v[194:197], v154 offset:3072
	v_lshl_add_u64 v[154:155], s[14:15], 0, v[136:137]
	s_add_i32 m0, s37, 0xc000
	ds_read_b128 v[198:201], v145
	ds_read_b128 v[202:205], v145 offset:1024
	ds_read_b128 v[206:209], v145 offset:2048
	ds_read_b128 v[210:213], v145 offset:3072
	ds_read_b128 v[214:217], v145 offset:4096
	ds_read_b128 v[218:221], v145 offset:5120
	ds_read_b128 v[222:225], v145 offset:6144
	ds_read_b128 v[226:229], v145 offset:7168
	global_load_lds_dwordx4 v[154:155], off
	v_lshl_add_u64 v[154:155], s[14:15], 0, v[138:139]
	s_add_i32 m0, s37, 0xe000
	s_nop 0
	global_load_lds_dwordx4 v[154:155], off
	s_setprio 0
	s_waitcnt vmcnt(8) lgkmcnt(0)
	s_barrier
	s_setprio 1
	v_mfma_f32_16x16x32_bf16 v[126:129], v[146:149], v[198:201], v[126:129]
	v_mfma_f32_16x16x32_bf16 v[122:125], v[162:165], v[198:201], v[122:125]
	v_mfma_f32_16x16x32_bf16 v[110:113], v[146:149], v[206:209], v[110:113]
	v_mfma_f32_16x16x32_bf16 v[106:109], v[162:165], v[206:209], v[106:109]
	v_mfma_f32_16x16x32_bf16 v[92:95], v[146:149], v[214:217], v[92:95]
	v_mfma_f32_16x16x32_bf16 v[88:91], v[162:165], v[214:217], v[88:91]
	v_mfma_f32_16x16x32_bf16 v[76:79], v[146:149], v[222:225], v[76:79]
	v_mfma_f32_16x16x32_bf16 v[72:75], v[162:165], v[222:225], v[72:75]
	v_mfma_f32_16x16x32_bf16 v[126:129], v[150:153], v[202:205], v[126:129]
	v_mfma_f32_16x16x32_bf16 v[122:125], v[166:169], v[202:205], v[122:125]
	v_mfma_f32_16x16x32_bf16 v[110:113], v[150:153], v[210:213], v[110:113]
	v_mfma_f32_16x16x32_bf16 v[106:109], v[166:169], v[210:213], v[106:109]
	v_mfma_f32_16x16x32_bf16 v[92:95], v[150:153], v[218:221], v[92:95]
	v_mfma_f32_16x16x32_bf16 v[88:91], v[166:169], v[218:221], v[88:91]
	v_mfma_f32_16x16x32_bf16 v[76:79], v[150:153], v[226:229], v[76:79]
	v_mfma_f32_16x16x32_bf16 v[72:75], v[166:169], v[226:229], v[72:75]
	s_setprio 0
	s_setprio 1
	v_mfma_f32_16x16x32_bf16 v[118:121], v[170:173], v[198:201], v[118:121]
	v_mfma_f32_16x16x32_bf16 v[114:117], v[190:193], v[198:201], v[114:117]
	v_mfma_f32_16x16x32_bf16 v[102:105], v[170:173], v[206:209], v[102:105]
	v_mfma_f32_16x16x32_bf16 v[98:101], v[190:193], v[206:209], v[98:101]
	v_mfma_f32_16x16x32_bf16 v[84:87], v[170:173], v[214:217], v[84:87]
	v_mfma_f32_16x16x32_bf16 v[80:83], v[190:193], v[214:217], v[80:83]
	v_mfma_f32_16x16x32_bf16 v[68:71], v[170:173], v[222:225], v[68:71]
	v_mfma_f32_16x16x32_bf16 v[64:67], v[190:193], v[222:225], v[64:67]
	v_mfma_f32_16x16x32_bf16 v[118:121], v[186:189], v[202:205], v[118:121]
	v_mfma_f32_16x16x32_bf16 v[114:117], v[194:197], v[202:205], v[114:117]
	v_mfma_f32_16x16x32_bf16 v[102:105], v[186:189], v[210:213], v[102:105]
	v_mfma_f32_16x16x32_bf16 v[98:101], v[194:197], v[210:213], v[98:101]
	v_mfma_f32_16x16x32_bf16 v[84:87], v[186:189], v[218:221], v[84:87]
	v_mfma_f32_16x16x32_bf16 v[80:83], v[194:197], v[218:221], v[80:83]
	v_mfma_f32_16x16x32_bf16 v[68:71], v[186:189], v[226:229], v[68:71]
	v_mfma_f32_16x16x32_bf16 v[64:67], v[194:197], v[226:229], v[64:67]
	s_setprio 0
	s_barrier
	s_setprio 2
	s_add_i32 s54, s54, s36
	v_lshl_add_u64 v[154:155], s[26:27], 0, v[96:97]
	s_mov_b32 m0, s54
	ds_read_b128 v[198:201], v145 offset:16384
	ds_read_b128 v[202:205], v145 offset:17408
	ds_read_b128 v[206:209], v145 offset:18432
	ds_read_b128 v[210:213], v145 offset:19456
	ds_read_b128 v[214:217], v145 offset:20480
	ds_read_b128 v[218:221], v145 offset:21504
	ds_read_b128 v[222:225], v145 offset:22528
	ds_read_b128 v[226:229], v145 offset:23552
	global_load_lds_dwordx4 v[154:155], off
	s_add_i32 m0, s54, 0x2000
	s_add_u32 s54, s26, 0x40000
	v_lshl_add_u64 v[156:157], s[26:27], 0, v[130:131]
	s_addc_u32 s55, s27, 0
	s_add_i32 s56, s56, s36
	global_load_lds_dwordx4 v[156:157], off
	v_lshl_add_u64 v[158:159], s[54:55], 0, v[96:97]
	s_mov_b32 m0, s56
	v_lshl_add_u64 v[182:183], s[28:29], 0, v[132:133]
	global_load_lds_dwordx4 v[158:159], off
	v_lshl_add_u64 v[158:159], s[54:55], 0, v[130:131]
	s_add_i32 m0, s56, 0x2000
	s_nop 0
	global_load_lds_dwordx4 v[158:159], off
	v_lshl_add_u64 v[158:159], s[28:29], 0, v[134:135]
	s_mov_b32 m0, s37
	s_nop 0
	global_load_lds_dwordx4 v[158:159], off
	s_mov_b32 m0, s38
	s_nop 0
	global_load_lds_dwordx4 v[182:183], off
	s_setprio 0
	s_waitcnt vmcnt(8) lgkmcnt(0)
	s_barrier
	s_setprio 1
	v_mfma_f32_16x16x32_bf16 v[60:63], v[146:149], v[198:201], v[60:63]
	v_mfma_f32_16x16x32_bf16 v[56:59], v[162:165], v[198:201], v[56:59]
	v_mfma_f32_16x16x32_bf16 v[44:47], v[146:149], v[206:209], v[44:47]
	v_mfma_f32_16x16x32_bf16 v[40:43], v[162:165], v[206:209], v[40:43]
	v_mfma_f32_16x16x32_bf16 v[28:31], v[146:149], v[214:217], v[28:31]
	v_mfma_f32_16x16x32_bf16 v[24:27], v[162:165], v[214:217], v[24:27]
	v_mfma_f32_16x16x32_bf16 v[12:15], v[146:149], v[222:225], v[12:15]
	v_mfma_f32_16x16x32_bf16 v[4:7], v[162:165], v[222:225], v[4:7]
	v_mfma_f32_16x16x32_bf16 v[60:63], v[150:153], v[202:205], v[60:63]
	v_mfma_f32_16x16x32_bf16 v[56:59], v[166:169], v[202:205], v[56:59]
	v_mfma_f32_16x16x32_bf16 v[44:47], v[150:153], v[210:213], v[44:47]
	v_mfma_f32_16x16x32_bf16 v[40:43], v[166:169], v[210:213], v[40:43]
	v_mfma_f32_16x16x32_bf16 v[28:31], v[150:153], v[218:221], v[28:31]
	v_mfma_f32_16x16x32_bf16 v[24:27], v[166:169], v[218:221], v[24:27]
	v_mfma_f32_16x16x32_bf16 v[12:15], v[150:153], v[226:229], v[12:15]
	v_mfma_f32_16x16x32_bf16 v[4:7], v[166:169], v[226:229], v[4:7]
	s_setprio 0
	s_setprio 1
	v_mfma_f32_16x16x32_bf16 v[52:55], v[170:173], v[198:201], v[52:55]
	v_mfma_f32_16x16x32_bf16 v[48:51], v[190:193], v[198:201], v[48:51]
	v_mfma_f32_16x16x32_bf16 v[36:39], v[170:173], v[206:209], v[36:39]
	v_mfma_f32_16x16x32_bf16 v[32:35], v[190:193], v[206:209], v[32:35]
	v_mfma_f32_16x16x32_bf16 v[20:23], v[170:173], v[214:217], v[20:23]
	v_mfma_f32_16x16x32_bf16 v[16:19], v[190:193], v[214:217], v[16:19]
	v_mfma_f32_16x16x32_bf16 v[8:11], v[170:173], v[222:225], v[8:11]
	v_mfma_f32_16x16x32_bf16 v[0:3], v[190:193], v[222:225], v[0:3]
	v_mfma_f32_16x16x32_bf16 v[52:55], v[186:189], v[202:205], v[52:55]
	v_mfma_f32_16x16x32_bf16 v[48:51], v[194:197], v[202:205], v[48:51]
	v_mfma_f32_16x16x32_bf16 v[36:39], v[186:189], v[210:213], v[36:39]
	v_mfma_f32_16x16x32_bf16 v[32:35], v[194:197], v[210:213], v[32:35]
	v_mfma_f32_16x16x32_bf16 v[20:23], v[186:189], v[218:221], v[20:23]
	v_mfma_f32_16x16x32_bf16 v[16:19], v[194:197], v[218:221], v[16:19]
	v_mfma_f32_16x16x32_bf16 v[8:11], v[186:189], v[226:229], v[8:11]
	v_mfma_f32_16x16x32_bf16 v[0:3], v[194:197], v[226:229], v[0:3]
	s_setprio 0
	s_barrier
	s_setprio 2
	s_add_i32 s54, 0, 0x18000
	s_add_i32 s55, 0, 0x1c000
	v_add_u32_e32 v166, s54, v141
	v_add_u32_e32 v184, s55, v141
	ds_read_b128 v[146:149], v166
	ds_read_b128 v[150:153], v166 offset:1024
	ds_read_b128 v[162:165], v166 offset:2048
	ds_read_b128 v[166:169], v166 offset:3072
	ds_read_b128 v[170:173], v184
	ds_read_b128 v[186:189], v184 offset:1024
	ds_read_b128 v[190:193], v184 offset:2048
	ds_read_b128 v[194:197], v184 offset:3072
	s_add_u32 s28, s28, 0x40000
	s_addc_u32 s29, s29, 0
	s_mov_b32 m0, s39
	v_lshl_add_u64 v[184:185], s[28:29], 0, v[134:135]
	ds_read_b128 v[198:201], v145 offset:32768
	ds_read_b128 v[202:205], v145 offset:33792
	ds_read_b128 v[206:209], v145 offset:34816
	ds_read_b128 v[210:213], v145 offset:35840
	ds_read_b128 v[214:217], v145 offset:36864
	ds_read_b128 v[218:221], v145 offset:37888
	ds_read_b128 v[222:225], v145 offset:38912
	ds_read_b128 v[226:229], v145 offset:39936
	global_load_lds_dwordx4 v[184:185], off
	v_lshl_add_u64 v[184:185], s[28:29], 0, v[132:133]
	s_mov_b32 m0, s40
	s_nop 0
	global_load_lds_dwordx4 v[184:185], off
	s_setprio 0
	s_waitcnt vmcnt(8) lgkmcnt(0)
	s_barrier
	s_setprio 1
	v_mfma_f32_16x16x32_bf16 v[126:129], v[146:149], v[198:201], v[126:129]
	v_mfma_f32_16x16x32_bf16 v[122:125], v[162:165], v[198:201], v[122:125]
	v_mfma_f32_16x16x32_bf16 v[110:113], v[146:149], v[206:209], v[110:113]
	v_mfma_f32_16x16x32_bf16 v[106:109], v[162:165], v[206:209], v[106:109]
	v_mfma_f32_16x16x32_bf16 v[92:95], v[146:149], v[214:217], v[92:95]
	v_mfma_f32_16x16x32_bf16 v[88:91], v[162:165], v[214:217], v[88:91]
	v_mfma_f32_16x16x32_bf16 v[76:79], v[146:149], v[222:225], v[76:79]
	v_mfma_f32_16x16x32_bf16 v[72:75], v[162:165], v[222:225], v[72:75]
	v_mfma_f32_16x16x32_bf16 v[126:129], v[150:153], v[202:205], v[126:129]
	v_mfma_f32_16x16x32_bf16 v[122:125], v[166:169], v[202:205], v[122:125]
	v_mfma_f32_16x16x32_bf16 v[110:113], v[150:153], v[210:213], v[110:113]
	v_mfma_f32_16x16x32_bf16 v[106:109], v[166:169], v[210:213], v[106:109]
	v_mfma_f32_16x16x32_bf16 v[92:95], v[150:153], v[218:221], v[92:95]
	v_mfma_f32_16x16x32_bf16 v[88:91], v[166:169], v[218:221], v[88:91]
	v_mfma_f32_16x16x32_bf16 v[76:79], v[150:153], v[226:229], v[76:79]
	v_mfma_f32_16x16x32_bf16 v[72:75], v[166:169], v[226:229], v[72:75]
	s_setprio 0
	s_setprio 1
	v_mfma_f32_16x16x32_bf16 v[118:121], v[170:173], v[198:201], v[118:121]
	v_mfma_f32_16x16x32_bf16 v[114:117], v[190:193], v[198:201], v[114:117]
	v_mfma_f32_16x16x32_bf16 v[102:105], v[170:173], v[206:209], v[102:105]
	v_mfma_f32_16x16x32_bf16 v[98:101], v[190:193], v[206:209], v[98:101]
	v_mfma_f32_16x16x32_bf16 v[84:87], v[170:173], v[214:217], v[84:87]
	v_mfma_f32_16x16x32_bf16 v[80:83], v[190:193], v[214:217], v[80:83]
	v_mfma_f32_16x16x32_bf16 v[68:71], v[170:173], v[222:225], v[68:71]
	v_mfma_f32_16x16x32_bf16 v[64:67], v[190:193], v[222:225], v[64:67]
	v_mfma_f32_16x16x32_bf16 v[118:121], v[186:189], v[202:205], v[118:121]
	v_mfma_f32_16x16x32_bf16 v[114:117], v[194:197], v[202:205], v[114:117]
	v_mfma_f32_16x16x32_bf16 v[102:105], v[186:189], v[210:213], v[102:105]
	v_mfma_f32_16x16x32_bf16 v[98:101], v[194:197], v[210:213], v[98:101]
	v_mfma_f32_16x16x32_bf16 v[84:87], v[186:189], v[218:221], v[84:87]
	v_mfma_f32_16x16x32_bf16 v[80:83], v[194:197], v[218:221], v[80:83]
	v_mfma_f32_16x16x32_bf16 v[68:71], v[186:189], v[226:229], v[68:71]
	v_mfma_f32_16x16x32_bf16 v[64:67], v[194:197], v[226:229], v[64:67]
	s_setprio 0
	s_barrier
	s_setprio 2
	s_add_i32 s28, s54, s36
	v_lshl_add_u64 v[154:155], v[154:155], 0, s[16:17]
	s_mov_b32 m0, s28
	ds_read_b128 v[198:201], v145 offset:49152
	ds_read_b128 v[202:205], v145 offset:50176
	ds_read_b128 v[206:209], v145 offset:51200
	ds_read_b128 v[210:213], v145 offset:52224
	ds_read_b128 v[214:217], v145 offset:53248
	ds_read_b128 v[218:221], v145 offset:54272
	ds_read_b128 v[222:225], v145 offset:55296
	ds_read_b128 v[226:229], v145 offset:56320
	global_load_lds_dwordx4 v[154:155], off
	s_add_i32 m0, s28, 0x2000
	s_add_u32 s26, s26, 0x40080
	v_lshl_add_u64 v[154:155], v[156:157], 0, s[16:17]
	s_addc_u32 s27, s27, 0
	s_add_i32 s28, s55, s36
	global_load_lds_dwordx4 v[154:155], off
	v_lshl_add_u64 v[154:155], s[26:27], 0, v[96:97]
	s_mov_b32 m0, s28
	s_nop 0
	global_load_lds_dwordx4 v[154:155], off
	v_lshl_add_u64 v[154:155], s[26:27], 0, v[130:131]
	s_add_i32 m0, s28, 0x2000
	s_nop 0
	global_load_lds_dwordx4 v[154:155], off
	v_lshl_add_u64 v[154:155], v[158:159], 0, s[16:17]
	s_mov_b32 m0, s41
	s_nop 0
	global_load_lds_dwordx4 v[154:155], off
	v_lshl_add_u64 v[154:155], v[182:183], 0, s[16:17]
	s_mov_b32 m0, s42
	s_nop 0
	global_load_lds_dwordx4 v[154:155], off
	s_setprio 0
	s_waitcnt vmcnt(8) lgkmcnt(0)
	s_barrier
	s_setprio 1
	v_mfma_f32_16x16x32_bf16 v[60:63], v[146:149], v[198:201], v[60:63]
	v_mfma_f32_16x16x32_bf16 v[56:59], v[162:165], v[198:201], v[56:59]
	v_mfma_f32_16x16x32_bf16 v[44:47], v[146:149], v[206:209], v[44:47]
	v_mfma_f32_16x16x32_bf16 v[40:43], v[162:165], v[206:209], v[40:43]
	v_mfma_f32_16x16x32_bf16 v[28:31], v[146:149], v[214:217], v[28:31]
	v_mfma_f32_16x16x32_bf16 v[24:27], v[162:165], v[214:217], v[24:27]
	v_mfma_f32_16x16x32_bf16 v[12:15], v[146:149], v[222:225], v[12:15]
	v_mfma_f32_16x16x32_bf16 v[4:7], v[162:165], v[222:225], v[4:7]
	v_mfma_f32_16x16x32_bf16 v[60:63], v[150:153], v[202:205], v[60:63]
	v_mfma_f32_16x16x32_bf16 v[56:59], v[166:169], v[202:205], v[56:59]
	v_mfma_f32_16x16x32_bf16 v[44:47], v[150:153], v[210:213], v[44:47]
	v_mfma_f32_16x16x32_bf16 v[40:43], v[166:169], v[210:213], v[40:43]
	v_mfma_f32_16x16x32_bf16 v[28:31], v[150:153], v[218:221], v[28:31]
	v_mfma_f32_16x16x32_bf16 v[24:27], v[166:169], v[218:221], v[24:27]
	v_mfma_f32_16x16x32_bf16 v[12:15], v[150:153], v[226:229], v[12:15]
	v_mfma_f32_16x16x32_bf16 v[4:7], v[166:169], v[226:229], v[4:7]
	s_setprio 0
	s_setprio 1
	v_mfma_f32_16x16x32_bf16 v[52:55], v[170:173], v[198:201], v[52:55]
	v_mfma_f32_16x16x32_bf16 v[48:51], v[190:193], v[198:201], v[48:51]
	v_mfma_f32_16x16x32_bf16 v[36:39], v[170:173], v[206:209], v[36:39]
	v_mfma_f32_16x16x32_bf16 v[32:35], v[190:193], v[206:209], v[32:35]
	v_mfma_f32_16x16x32_bf16 v[20:23], v[170:173], v[214:217], v[20:23]
	v_mfma_f32_16x16x32_bf16 v[16:19], v[190:193], v[214:217], v[16:19]
	v_mfma_f32_16x16x32_bf16 v[8:11], v[170:173], v[222:225], v[8:11]
	v_mfma_f32_16x16x32_bf16 v[0:3], v[190:193], v[222:225], v[0:3]
	v_mfma_f32_16x16x32_bf16 v[52:55], v[186:189], v[202:205], v[52:55]
	v_mfma_f32_16x16x32_bf16 v[48:51], v[194:197], v[202:205], v[48:51]
	v_mfma_f32_16x16x32_bf16 v[36:39], v[186:189], v[210:213], v[36:39]
	v_mfma_f32_16x16x32_bf16 v[32:35], v[194:197], v[210:213], v[32:35]
	v_mfma_f32_16x16x32_bf16 v[20:23], v[186:189], v[218:221], v[20:23]
	v_mfma_f32_16x16x32_bf16 v[16:19], v[194:197], v[218:221], v[16:19]
	v_mfma_f32_16x16x32_bf16 v[8:11], v[186:189], v[226:229], v[8:11]
	v_mfma_f32_16x16x32_bf16 v[0:3], v[194:197], v[226:229], v[0:3]
	s_setprio 0
	s_barrier
	s_setprio 2
	s_add_i32 s53, s53, 2
	s_add_u32 s14, s14, 0x100
	s_addc_u32 s15, s15, 0
	s_add_u32 s51, s51, 0x100
	s_addc_u32 s52, s52, 0
	s_cmp_gt_u32 s53, 13
	s_cbranch_scc0 .LBB0_271
	s_and_b64 vcc, exec, s[12:13]
	s_cbranch_vccz .LBB0_274
	s_barrier

.LBB0_361:
	s_add_u32 s34, s30, 0xfffc0080
	s_addc_u32 s35, s31, -1
	s_add_i32 s62, 0, 0x10000
	s_cmp_eq_u32 s61, 12
	s_cselect_b32 s37, s25, s35
	s_cselect_b32 s36, s57, s34
	v_add_u32_e32 v96, s62, v151
	s_cselect_b32 s35, s15, s60
	s_cselect_b32 s34, s58, s59
	s_add_i32 s64, 0, 0x14000
	ds_read_b128 v[164:167], v96
	ds_read_b128 v[168:171], v96 offset:1024
	ds_read_b128 v[186:189], v96 offset:2048
	ds_read_b128 v[190:193], v96 offset:3072
	v_add_u32_e32 v96, s64, v151
	ds_read_b128 v[194:197], v96
	ds_read_b128 v[198:201], v96 offset:1024
	ds_read_b128 v[202:205], v96 offset:2048
	ds_read_b128 v[206:209], v96 offset:3072
	v_lshl_add_u64 v[154:155], s[30:31], 0, v[146:147]
	s_add_i32 m0, s43, 0xc000
	ds_read_b128 v[210:213], v162
	ds_read_b128 v[214:217], v162 offset:1024
	ds_read_b128 v[218:221], v162 offset:2048
	ds_read_b128 v[222:225], v162 offset:3072
	ds_read_b128 v[226:229], v162 offset:4096
	ds_read_b128 v[230:233], v162 offset:5120
	ds_read_b128 v[242:245], v162 offset:6144
	ds_read_b128 v[246:249], v162 offset:7168
	global_load_lds_dwordx4 v[154:155], off
	v_lshl_add_u64 v[154:155], s[30:31], 0, v[148:149]
	s_add_i32 m0, s43, 0xe000
	s_nop 0
	global_load_lds_dwordx4 v[154:155], off
	s_setprio 0
	s_waitcnt vmcnt(8) lgkmcnt(0)
	s_barrier
	s_setprio 1
	v_mfma_f32_16x16x32_bf16 v[126:129], v[164:167], v[210:213], v[126:129]
	v_mfma_f32_16x16x32_bf16 v[122:125], v[186:189], v[210:213], v[122:125]
	v_mfma_f32_16x16x32_bf16 v[118:121], v[164:167], v[218:221], v[118:121]
	v_mfma_f32_16x16x32_bf16 v[114:117], v[186:189], v[218:221], v[114:117]
	v_mfma_f32_16x16x32_bf16 v[110:113], v[164:167], v[226:229], v[110:113]
	v_mfma_f32_16x16x32_bf16 v[106:109], v[186:189], v[226:229], v[106:109]
	v_mfma_f32_16x16x32_bf16 v[102:105], v[164:167], v[242:245], v[102:105]
	v_mfma_f32_16x16x32_bf16 v[98:101], v[186:189], v[242:245], v[98:101]
	v_mfma_f32_16x16x32_bf16 v[126:129], v[168:171], v[214:217], v[126:129]
	v_mfma_f32_16x16x32_bf16 v[122:125], v[190:193], v[214:217], v[122:125]
	v_mfma_f32_16x16x32_bf16 v[118:121], v[168:171], v[222:225], v[118:121]
	v_mfma_f32_16x16x32_bf16 v[114:117], v[190:193], v[222:225], v[114:117]
	v_mfma_f32_16x16x32_bf16 v[110:113], v[168:171], v[230:233], v[110:113]
	v_mfma_f32_16x16x32_bf16 v[106:109], v[190:193], v[230:233], v[106:109]
	v_mfma_f32_16x16x32_bf16 v[102:105], v[168:171], v[246:249], v[102:105]
	v_mfma_f32_16x16x32_bf16 v[98:101], v[190:193], v[246:249], v[98:101]
	s_setprio 0
	s_setprio 1
	v_mfma_f32_16x16x32_bf16 v[76:79], v[194:197], v[210:213], v[76:79]
	v_mfma_f32_16x16x32_bf16 v[64:67], v[202:205], v[210:213], v[64:67]
	v_mfma_f32_16x16x32_bf16 v[60:63], v[194:197], v[218:221], v[60:63]
	v_mfma_f32_16x16x32_bf16 v[52:55], v[202:205], v[218:221], v[52:55]
	v_mfma_f32_16x16x32_bf16 v[44:47], v[194:197], v[226:229], v[44:47]
	v_mfma_f32_16x16x32_bf16 v[40:43], v[202:205], v[226:229], v[40:43]
	v_mfma_f32_16x16x32_bf16 v[36:39], v[194:197], v[242:245], v[36:39]
	v_mfma_f32_16x16x32_bf16 v[32:35], v[202:205], v[242:245], v[32:35]
	v_mfma_f32_16x16x32_bf16 v[76:79], v[198:201], v[214:217], v[76:79]
	v_mfma_f32_16x16x32_bf16 v[64:67], v[206:209], v[214:217], v[64:67]
	v_mfma_f32_16x16x32_bf16 v[60:63], v[198:201], v[222:225], v[60:63]
	v_mfma_f32_16x16x32_bf16 v[52:55], v[206:209], v[222:225], v[52:55]
	v_mfma_f32_16x16x32_bf16 v[44:47], v[198:201], v[230:233], v[44:47]
	v_mfma_f32_16x16x32_bf16 v[40:43], v[206:209], v[230:233], v[40:43]
	v_mfma_f32_16x16x32_bf16 v[36:39], v[198:201], v[246:249], v[36:39]
	v_mfma_f32_16x16x32_bf16 v[32:35], v[206:209], v[246:249], v[32:35]
	s_setprio 0
	s_barrier
	s_setprio 2
	s_add_i32 s62, s62, s40
	v_lshl_add_u64 v[154:155], s[34:35], 0, v[134:135]
	s_mov_b32 m0, s62
	ds_read_b128 v[210:213], v162 offset:16384
	ds_read_b128 v[214:217], v162 offset:17408
	ds_read_b128 v[218:221], v162 offset:18432
	ds_read_b128 v[222:225], v162 offset:19456
	ds_read_b128 v[226:229], v162 offset:20480
	ds_read_b128 v[230:233], v162 offset:21504
	ds_read_b128 v[242:245], v162 offset:22528
	ds_read_b128 v[246:249], v162 offset:23552
	global_load_lds_dwordx4 v[154:155], off
	s_add_i32 m0, s62, 0x2000
	s_add_u32 s62, s34, 0x40000
	v_lshl_add_u64 v[156:157], s[34:35], 0, v[130:131]
	s_addc_u32 s63, s35, 0
	s_add_i32 s64, s64, s40
	global_load_lds_dwordx4 v[156:157], off
	v_lshl_add_u64 v[158:159], s[62:63], 0, v[134:135]
	s_mov_b32 m0, s64
	v_lshl_add_u64 v[172:173], s[36:37], 0, v[132:133]
	global_load_lds_dwordx4 v[158:159], off
	v_lshl_add_u64 v[158:159], s[62:63], 0, v[130:131]
	s_add_i32 m0, s64, 0x2000
	s_nop 0
	global_load_lds_dwordx4 v[158:159], off
	v_lshl_add_u64 v[158:159], s[36:37], 0, v[136:137]
	s_mov_b32 m0, s43
	s_nop 0
	global_load_lds_dwordx4 v[158:159], off
	s_mov_b32 m0, s44
	s_nop 0
	global_load_lds_dwordx4 v[172:173], off
	s_setprio 0
	s_waitcnt vmcnt(8) lgkmcnt(0)
	s_barrier
	s_setprio 1
	v_mfma_f32_16x16x32_bf16 v[92:95], v[164:167], v[210:213], v[92:95]
	v_mfma_f32_16x16x32_bf16 v[88:91], v[186:189], v[210:213], v[88:91]
	v_mfma_f32_16x16x32_bf16 v[84:87], v[164:167], v[218:221], v[84:87]
	v_mfma_f32_16x16x32_bf16 v[80:83], v[186:189], v[218:221], v[80:83]
	v_mfma_f32_16x16x32_bf16 v[72:75], v[164:167], v[226:229], v[72:75]
	v_mfma_f32_16x16x32_bf16 v[68:71], v[186:189], v[226:229], v[68:71]
	v_mfma_f32_16x16x32_bf16 v[56:59], v[164:167], v[242:245], v[56:59]
	v_mfma_f32_16x16x32_bf16 v[48:51], v[186:189], v[242:245], v[48:51]
	v_mfma_f32_16x16x32_bf16 v[92:95], v[168:171], v[214:217], v[92:95]
	v_mfma_f32_16x16x32_bf16 v[88:91], v[190:193], v[214:217], v[88:91]
	v_mfma_f32_16x16x32_bf16 v[84:87], v[168:171], v[222:225], v[84:87]
	v_mfma_f32_16x16x32_bf16 v[80:83], v[190:193], v[222:225], v[80:83]
	v_mfma_f32_16x16x32_bf16 v[72:75], v[168:171], v[230:233], v[72:75]
	v_mfma_f32_16x16x32_bf16 v[68:71], v[190:193], v[230:233], v[68:71]
	v_mfma_f32_16x16x32_bf16 v[56:59], v[168:171], v[246:249], v[56:59]
	v_mfma_f32_16x16x32_bf16 v[48:51], v[190:193], v[246:249], v[48:51]
	s_setprio 0
	s_setprio 1
	v_mfma_f32_16x16x32_bf16 v[28:31], v[194:197], v[210:213], v[28:31]
	v_mfma_f32_16x16x32_bf16 v[24:27], v[202:205], v[210:213], v[24:27]
	v_mfma_f32_16x16x32_bf16 v[20:23], v[194:197], v[218:221], v[20:23]
	v_mfma_f32_16x16x32_bf16 v[16:19], v[202:205], v[218:221], v[16:19]
	v_mfma_f32_16x16x32_bf16 v[12:15], v[194:197], v[226:229], v[12:15]
	v_mfma_f32_16x16x32_bf16 v[8:11], v[202:205], v[226:229], v[8:11]
	v_mfma_f32_16x16x32_bf16 v[4:7], v[194:197], v[242:245], v[4:7]
	v_mfma_f32_16x16x32_bf16 v[0:3], v[202:205], v[242:245], v[0:3]
	v_mfma_f32_16x16x32_bf16 v[28:31], v[198:201], v[214:217], v[28:31]
	v_mfma_f32_16x16x32_bf16 v[24:27], v[206:209], v[214:217], v[24:27]
	v_mfma_f32_16x16x32_bf16 v[20:23], v[198:201], v[222:225], v[20:23]
	v_mfma_f32_16x16x32_bf16 v[16:19], v[206:209], v[222:225], v[16:19]
	v_mfma_f32_16x16x32_bf16 v[12:15], v[198:201], v[230:233], v[12:15]
	v_mfma_f32_16x16x32_bf16 v[8:11], v[206:209], v[230:233], v[8:11]
	v_mfma_f32_16x16x32_bf16 v[4:7], v[198:201], v[246:249], v[4:7]
	v_mfma_f32_16x16x32_bf16 v[0:3], v[206:209], v[246:249], v[0:3]
	s_setprio 0
	s_barrier
	s_setprio 2
	s_add_i32 s62, 0, 0x18000
	v_add_u32_e32 v96, s62, v151
	s_add_i32 s63, 0, 0x1c000
	ds_read_b128 v[164:167], v96
	ds_read_b128 v[168:171], v96 offset:1024
	ds_read_b128 v[186:189], v96 offset:2048
	ds_read_b128 v[190:193], v96 offset:3072
	v_add_u32_e32 v96, s63, v151
	ds_read_b128 v[194:197], v96
	ds_read_b128 v[198:201], v96 offset:1024
	ds_read_b128 v[202:205], v96 offset:2048
	ds_read_b128 v[206:209], v96 offset:3072
	s_add_u32 s36, s36, 0x40000
	s_addc_u32 s37, s37, 0
	s_mov_b32 m0, s45
	v_lshl_add_u64 v[182:183], s[36:37], 0, v[136:137]
	ds_read_b128 v[210:213], v162 offset:32768
	ds_read_b128 v[214:217], v162 offset:33792
	ds_read_b128 v[218:221], v162 offset:34816
	ds_read_b128 v[222:225], v162 offset:35840
	ds_read_b128 v[226:229], v162 offset:36864
	ds_read_b128 v[230:233], v162 offset:37888
	ds_read_b128 v[242:245], v162 offset:38912
	ds_read_b128 v[246:249], v162 offset:39936
	global_load_lds_dwordx4 v[182:183], off
	v_lshl_add_u64 v[182:183], s[36:37], 0, v[132:133]
	s_mov_b32 m0, s46
	s_nop 0
	global_load_lds_dwordx4 v[182:183], off
	s_setprio 0
	s_waitcnt vmcnt(8) lgkmcnt(0)
	s_barrier
	s_setprio 1
	v_mfma_f32_16x16x32_bf16 v[126:129], v[164:167], v[210:213], v[126:129]
	v_mfma_f32_16x16x32_bf16 v[122:125], v[186:189], v[210:213], v[122:125]
	v_mfma_f32_16x16x32_bf16 v[118:121], v[164:167], v[218:221], v[118:121]
	v_mfma_f32_16x16x32_bf16 v[114:117], v[186:189], v[218:221], v[114:117]
	v_mfma_f32_16x16x32_bf16 v[110:113], v[164:167], v[226:229], v[110:113]
	v_mfma_f32_16x16x32_bf16 v[106:109], v[186:189], v[226:229], v[106:109]
	v_mfma_f32_16x16x32_bf16 v[102:105], v[164:167], v[242:245], v[102:105]
	v_mfma_f32_16x16x32_bf16 v[98:101], v[186:189], v[242:245], v[98:101]
	v_mfma_f32_16x16x32_bf16 v[126:129], v[168:171], v[214:217], v[126:129]
	v_mfma_f32_16x16x32_bf16 v[122:125], v[190:193], v[214:217], v[122:125]
	v_mfma_f32_16x16x32_bf16 v[118:121], v[168:171], v[222:225], v[118:121]
	v_mfma_f32_16x16x32_bf16 v[114:117], v[190:193], v[222:225], v[114:117]
	v_mfma_f32_16x16x32_bf16 v[110:113], v[168:171], v[230:233], v[110:113]
	v_mfma_f32_16x16x32_bf16 v[106:109], v[190:193], v[230:233], v[106:109]
	v_mfma_f32_16x16x32_bf16 v[102:105], v[168:171], v[246:249], v[102:105]
	v_mfma_f32_16x16x32_bf16 v[98:101], v[190:193], v[246:249], v[98:101]
	s_setprio 0
	s_setprio 1
	v_mfma_f32_16x16x32_bf16 v[76:79], v[194:197], v[210:213], v[76:79]
	v_mfma_f32_16x16x32_bf16 v[64:67], v[202:205], v[210:213], v[64:67]
	v_mfma_f32_16x16x32_bf16 v[60:63], v[194:197], v[218:221], v[60:63]
	v_mfma_f32_16x16x32_bf16 v[52:55], v[202:205], v[218:221], v[52:55]
	v_mfma_f32_16x16x32_bf16 v[44:47], v[194:197], v[226:229], v[44:47]
	v_mfma_f32_16x16x32_bf16 v[40:43], v[202:205], v[226:229], v[40:43]
	v_mfma_f32_16x16x32_bf16 v[36:39], v[194:197], v[242:245], v[36:39]
	v_mfma_f32_16x16x32_bf16 v[32:35], v[202:205], v[242:245], v[32:35]
	v_mfma_f32_16x16x32_bf16 v[76:79], v[198:201], v[214:217], v[76:79]
	v_mfma_f32_16x16x32_bf16 v[64:67], v[206:209], v[214:217], v[64:67]
	v_mfma_f32_16x16x32_bf16 v[60:63], v[198:201], v[222:225], v[60:63]
	v_mfma_f32_16x16x32_bf16 v[52:55], v[206:209], v[222:225], v[52:55]
	v_mfma_f32_16x16x32_bf16 v[44:47], v[198:201], v[230:233], v[44:47]
	v_mfma_f32_16x16x32_bf16 v[40:43], v[206:209], v[230:233], v[40:43]
	v_mfma_f32_16x16x32_bf16 v[36:39], v[198:201], v[246:249], v[36:39]
	v_mfma_f32_16x16x32_bf16 v[32:35], v[206:209], v[246:249], v[32:35]
	s_setprio 0
	s_barrier
	s_setprio 2
	s_add_i32 s36, s62, s40
	v_lshl_add_u64 v[154:155], v[154:155], 0, s[16:17]
	s_mov_b32 m0, s36
	ds_read_b128 v[210:213], v162 offset:49152
	ds_read_b128 v[214:217], v162 offset:50176
	ds_read_b128 v[218:221], v162 offset:51200
	ds_read_b128 v[222:225], v162 offset:52224
	ds_read_b128 v[226:229], v162 offset:53248
	ds_read_b128 v[230:233], v162 offset:54272
	ds_read_b128 v[242:245], v162 offset:55296
	ds_read_b128 v[246:249], v162 offset:56320
	global_load_lds_dwordx4 v[154:155], off
	s_add_i32 m0, s36, 0x2000
	s_add_u32 s34, s34, 0x40080
	v_lshl_add_u64 v[154:155], v[156:157], 0, s[16:17]
	s_addc_u32 s35, s35, 0
	s_add_i32 s36, s63, s40
	global_load_lds_dwordx4 v[154:155], off
	v_lshl_add_u64 v[154:155], s[34:35], 0, v[134:135]
	s_mov_b32 m0, s36
	s_nop 0
	global_load_lds_dwordx4 v[154:155], off
	v_lshl_add_u64 v[154:155], s[34:35], 0, v[130:131]
	s_add_i32 m0, s36, 0x2000
	s_nop 0
	global_load_lds_dwordx4 v[154:155], off
	v_lshl_add_u64 v[154:155], v[158:159], 0, s[16:17]
	s_mov_b32 m0, s50
	s_nop 0
	global_load_lds_dwordx4 v[154:155], off
	v_lshl_add_u64 v[154:155], v[172:173], 0, s[16:17]
	s_mov_b32 m0, s51
	s_nop 0
	global_load_lds_dwordx4 v[154:155], off
	s_setprio 0
	s_waitcnt vmcnt(8) lgkmcnt(0)
	s_barrier
	s_setprio 1
	v_mfma_f32_16x16x32_bf16 v[92:95], v[164:167], v[210:213], v[92:95]
	v_mfma_f32_16x16x32_bf16 v[88:91], v[186:189], v[210:213], v[88:91]
	v_mfma_f32_16x16x32_bf16 v[84:87], v[164:167], v[218:221], v[84:87]
	v_mfma_f32_16x16x32_bf16 v[80:83], v[186:189], v[218:221], v[80:83]
	v_mfma_f32_16x16x32_bf16 v[72:75], v[164:167], v[226:229], v[72:75]
	v_mfma_f32_16x16x32_bf16 v[68:71], v[186:189], v[226:229], v[68:71]
	v_mfma_f32_16x16x32_bf16 v[56:59], v[164:167], v[242:245], v[56:59]
	v_mfma_f32_16x16x32_bf16 v[48:51], v[186:189], v[242:245], v[48:51]
	v_mfma_f32_16x16x32_bf16 v[92:95], v[168:171], v[214:217], v[92:95]
	v_mfma_f32_16x16x32_bf16 v[88:91], v[190:193], v[214:217], v[88:91]
	v_mfma_f32_16x16x32_bf16 v[84:87], v[168:171], v[222:225], v[84:87]
	v_mfma_f32_16x16x32_bf16 v[80:83], v[190:193], v[222:225], v[80:83]
	v_mfma_f32_16x16x32_bf16 v[72:75], v[168:171], v[230:233], v[72:75]
	v_mfma_f32_16x16x32_bf16 v[68:71], v[190:193], v[230:233], v[68:71]
	v_mfma_f32_16x16x32_bf16 v[56:59], v[168:171], v[246:249], v[56:59]
	v_mfma_f32_16x16x32_bf16 v[48:51], v[190:193], v[246:249], v[48:51]
	s_setprio 0
	s_setprio 1
	v_mfma_f32_16x16x32_bf16 v[28:31], v[194:197], v[210:213], v[28:31]
	v_mfma_f32_16x16x32_bf16 v[24:27], v[202:205], v[210:213], v[24:27]
	v_mfma_f32_16x16x32_bf16 v[20:23], v[194:197], v[218:221], v[20:23]
	v_mfma_f32_16x16x32_bf16 v[16:19], v[202:205], v[218:221], v[16:19]
	v_mfma_f32_16x16x32_bf16 v[12:15], v[194:197], v[226:229], v[12:15]
	v_mfma_f32_16x16x32_bf16 v[8:11], v[202:205], v[226:229], v[8:11]
	v_mfma_f32_16x16x32_bf16 v[4:7], v[194:197], v[242:245], v[4:7]
	v_mfma_f32_16x16x32_bf16 v[0:3], v[202:205], v[242:245], v[0:3]
	v_mfma_f32_16x16x32_bf16 v[28:31], v[198:201], v[214:217], v[28:31]
	v_mfma_f32_16x16x32_bf16 v[24:27], v[206:209], v[214:217], v[24:27]
	v_mfma_f32_16x16x32_bf16 v[20:23], v[198:201], v[222:225], v[20:23]
	v_mfma_f32_16x16x32_bf16 v[16:19], v[206:209], v[222:225], v[16:19]
	v_mfma_f32_16x16x32_bf16 v[12:15], v[198:201], v[230:233], v[12:15]
	v_mfma_f32_16x16x32_bf16 v[8:11], v[206:209], v[230:233], v[8:11]
	v_mfma_f32_16x16x32_bf16 v[4:7], v[198:201], v[246:249], v[4:7]
	v_mfma_f32_16x16x32_bf16 v[0:3], v[206:209], v[246:249], v[0:3]
	s_setprio 0
	s_barrier
	s_setprio 2
	s_add_i32 s61, s61, 2
	s_add_u32 s30, s30, 0x100
	s_addc_u32 s31, s31, 0
	s_add_u32 s59, s59, 0x100
	s_addc_u32 s60, s60, 0
	s_cmp_gt_u32 s61, 13
	s_cbranch_scc0 .LBB0_361
	s_and_b64 vcc, exec, s[20:21]
	s_cbranch_vccz .LBB0_364
	s_barrier

.LBB0_393:
	s_add_u32 s26, s14, 0xfffc0080
	s_addc_u32 s27, s15, -1
	s_add_i32 s57, 0, 0x10000
	s_cmp_eq_u32 s56, 12
	s_cselect_b32 s29, s19, s27
	s_cselect_b32 s28, s52, s26
	v_add_u32_e32 v151, s57, v141
	s_cselect_b32 s27, s5, s55
	s_cselect_b32 s26, s53, s54
	s_add_i32 s60, 0, 0x14000
	ds_read_b128 v[162:165], v151
	ds_read_b128 v[166:169], v151 offset:1024
	ds_read_b128 v[170:173], v151 offset:2048
	ds_read_b128 v[186:189], v151 offset:3072
	v_add_u32_e32 v151, s60, v141
	ds_read_b128 v[190:193], v151
	ds_read_b128 v[194:197], v151 offset:1024
	ds_read_b128 v[198:201], v151 offset:2048
	ds_read_b128 v[202:205], v151 offset:3072
	v_lshl_add_u64 v[152:153], s[14:15], 0, v[146:147]
	s_add_i32 m0, s39, 0xc000
	ds_read_b128 v[206:209], v150
	ds_read_b128 v[210:213], v150 offset:1024
	ds_read_b128 v[214:217], v150 offset:2048
	ds_read_b128 v[218:221], v150 offset:3072
	ds_read_b128 v[222:225], v150 offset:4096
	ds_read_b128 v[226:229], v150 offset:5120
	ds_read_b128 v[230:233], v150 offset:6144
	ds_read_b128 v[242:245], v150 offset:7168
	global_load_lds_dwordx4 v[152:153], off
	v_lshl_add_u64 v[152:153], s[14:15], 0, v[148:149]
	s_add_i32 m0, s39, 0xe000
	s_nop 0
	global_load_lds_dwordx4 v[152:153], off
	s_setprio 0
	s_waitcnt vmcnt(8) lgkmcnt(0)
	s_barrier
	s_setprio 1
	v_mfma_f32_16x16x32_bf16 v[126:129], v[162:165], v[206:209], v[126:129]
	v_mfma_f32_16x16x32_bf16 v[122:125], v[170:173], v[206:209], v[122:125]
	v_mfma_f32_16x16x32_bf16 v[118:121], v[162:165], v[214:217], v[118:121]
	v_mfma_f32_16x16x32_bf16 v[114:117], v[170:173], v[214:217], v[114:117]
	v_mfma_f32_16x16x32_bf16 v[110:113], v[162:165], v[222:225], v[110:113]
	v_mfma_f32_16x16x32_bf16 v[106:109], v[170:173], v[222:225], v[106:109]
	v_mfma_f32_16x16x32_bf16 v[102:105], v[162:165], v[230:233], v[102:105]
	v_mfma_f32_16x16x32_bf16 v[98:101], v[170:173], v[230:233], v[98:101]
	v_mfma_f32_16x16x32_bf16 v[126:129], v[166:169], v[210:213], v[126:129]
	v_mfma_f32_16x16x32_bf16 v[122:125], v[186:189], v[210:213], v[122:125]
	v_mfma_f32_16x16x32_bf16 v[118:121], v[166:169], v[218:221], v[118:121]
	v_mfma_f32_16x16x32_bf16 v[114:117], v[186:189], v[218:221], v[114:117]
	v_mfma_f32_16x16x32_bf16 v[110:113], v[166:169], v[226:229], v[110:113]
	v_mfma_f32_16x16x32_bf16 v[106:109], v[186:189], v[226:229], v[106:109]
	v_mfma_f32_16x16x32_bf16 v[102:105], v[166:169], v[242:245], v[102:105]
	v_mfma_f32_16x16x32_bf16 v[98:101], v[186:189], v[242:245], v[98:101]
	s_setprio 0
	s_setprio 1
	v_mfma_f32_16x16x32_bf16 v[68:71], v[190:193], v[206:209], v[68:71]
	v_mfma_f32_16x16x32_bf16 v[64:67], v[198:201], v[206:209], v[64:67]
	v_mfma_f32_16x16x32_bf16 v[52:55], v[190:193], v[214:217], v[52:55]
	v_mfma_f32_16x16x32_bf16 v[48:51], v[198:201], v[214:217], v[48:51]
	v_mfma_f32_16x16x32_bf16 v[44:47], v[190:193], v[222:225], v[44:47]
	v_mfma_f32_16x16x32_bf16 v[40:43], v[198:201], v[222:225], v[40:43]
	v_mfma_f32_16x16x32_bf16 v[36:39], v[190:193], v[230:233], v[36:39]
	v_mfma_f32_16x16x32_bf16 v[32:35], v[198:201], v[230:233], v[32:35]
	v_mfma_f32_16x16x32_bf16 v[68:71], v[194:197], v[210:213], v[68:71]
	v_mfma_f32_16x16x32_bf16 v[64:67], v[202:205], v[210:213], v[64:67]
	v_mfma_f32_16x16x32_bf16 v[52:55], v[194:197], v[218:221], v[52:55]
	v_mfma_f32_16x16x32_bf16 v[48:51], v[202:205], v[218:221], v[48:51]
	v_mfma_f32_16x16x32_bf16 v[44:47], v[194:197], v[226:229], v[44:47]
	v_mfma_f32_16x16x32_bf16 v[40:43], v[202:205], v[226:229], v[40:43]
	v_mfma_f32_16x16x32_bf16 v[36:39], v[194:197], v[242:245], v[36:39]
	v_mfma_f32_16x16x32_bf16 v[32:35], v[202:205], v[242:245], v[32:35]
	s_setprio 0
	s_barrier
	s_setprio 2
	s_add_i32 s57, s57, s36
	v_lshl_add_u64 v[152:153], s[26:27], 0, v[96:97]
	s_mov_b32 m0, s57
	ds_read_b128 v[206:209], v150 offset:16384
	ds_read_b128 v[210:213], v150 offset:17408
	ds_read_b128 v[214:217], v150 offset:18432
	ds_read_b128 v[218:221], v150 offset:19456
	ds_read_b128 v[222:225], v150 offset:20480
	ds_read_b128 v[226:229], v150 offset:21504
	ds_read_b128 v[230:233], v150 offset:22528
	ds_read_b128 v[242:245], v150 offset:23552
	global_load_lds_dwordx4 v[152:153], off
	s_add_i32 m0, s57, 0x2000
	s_add_u32 s58, s26, 0x40000
	v_lshl_add_u64 v[154:155], s[26:27], 0, v[130:131]
	s_addc_u32 s59, s27, 0
	s_add_i32 s57, s60, s36
	global_load_lds_dwordx4 v[154:155], off
	v_lshl_add_u64 v[156:157], s[58:59], 0, v[96:97]
	s_mov_b32 m0, s57
	v_lshl_add_u64 v[158:159], s[28:29], 0, v[132:133]
	global_load_lds_dwordx4 v[156:157], off
	v_lshl_add_u64 v[156:157], s[58:59], 0, v[130:131]
	s_add_i32 m0, s57, 0x2000
	s_nop 0
	global_load_lds_dwordx4 v[156:157], off
	v_lshl_add_u64 v[156:157], s[28:29], 0, v[134:135]
	s_mov_b32 m0, s39
	s_nop 0
	global_load_lds_dwordx4 v[156:157], off
	s_mov_b32 m0, s40
	s_nop 0
	global_load_lds_dwordx4 v[158:159], off
	s_setprio 0
	s_waitcnt vmcnt(8) lgkmcnt(0)
	s_barrier
	s_setprio 1
	v_mfma_f32_16x16x32_bf16 v[92:95], v[162:165], v[206:209], v[92:95]
	v_mfma_f32_16x16x32_bf16 v[88:91], v[170:173], v[206:209], v[88:91]
	v_mfma_f32_16x16x32_bf16 v[84:87], v[162:165], v[214:217], v[84:87]
	v_mfma_f32_16x16x32_bf16 v[80:83], v[170:173], v[214:217], v[80:83]
	v_mfma_f32_16x16x32_bf16 v[76:79], v[162:165], v[222:225], v[76:79]
	v_mfma_f32_16x16x32_bf16 v[72:75], v[170:173], v[222:225], v[72:75]
	v_mfma_f32_16x16x32_bf16 v[60:63], v[162:165], v[230:233], v[60:63]
	v_mfma_f32_16x16x32_bf16 v[56:59], v[170:173], v[230:233], v[56:59]
	v_mfma_f32_16x16x32_bf16 v[92:95], v[166:169], v[210:213], v[92:95]
	v_mfma_f32_16x16x32_bf16 v[88:91], v[186:189], v[210:213], v[88:91]
	v_mfma_f32_16x16x32_bf16 v[84:87], v[166:169], v[218:221], v[84:87]
	v_mfma_f32_16x16x32_bf16 v[80:83], v[186:189], v[218:221], v[80:83]
	v_mfma_f32_16x16x32_bf16 v[76:79], v[166:169], v[226:229], v[76:79]
	v_mfma_f32_16x16x32_bf16 v[72:75], v[186:189], v[226:229], v[72:75]
	v_mfma_f32_16x16x32_bf16 v[60:63], v[166:169], v[242:245], v[60:63]
	v_mfma_f32_16x16x32_bf16 v[56:59], v[186:189], v[242:245], v[56:59]
	s_setprio 0
	s_setprio 1
	v_mfma_f32_16x16x32_bf16 v[28:31], v[190:193], v[206:209], v[28:31]
	v_mfma_f32_16x16x32_bf16 v[24:27], v[198:201], v[206:209], v[24:27]
	v_mfma_f32_16x16x32_bf16 v[20:23], v[190:193], v[214:217], v[20:23]
	v_mfma_f32_16x16x32_bf16 v[16:19], v[198:201], v[214:217], v[16:19]
	v_mfma_f32_16x16x32_bf16 v[12:15], v[190:193], v[222:225], v[12:15]
	v_mfma_f32_16x16x32_bf16 v[8:11], v[198:201], v[222:225], v[8:11]
	v_mfma_f32_16x16x32_bf16 v[4:7], v[190:193], v[230:233], v[4:7]
	v_mfma_f32_16x16x32_bf16 v[0:3], v[198:201], v[230:233], v[0:3]
	v_mfma_f32_16x16x32_bf16 v[28:31], v[194:197], v[210:213], v[28:31]
	v_mfma_f32_16x16x32_bf16 v[24:27], v[202:205], v[210:213], v[24:27]
	v_mfma_f32_16x16x32_bf16 v[20:23], v[194:197], v[218:221], v[20:23]
	v_mfma_f32_16x16x32_bf16 v[16:19], v[202:205], v[218:221], v[16:19]
	v_mfma_f32_16x16x32_bf16 v[12:15], v[194:197], v[226:229], v[12:15]
	v_mfma_f32_16x16x32_bf16 v[8:11], v[202:205], v[226:229], v[8:11]
	v_mfma_f32_16x16x32_bf16 v[4:7], v[194:197], v[242:245], v[4:7]
	v_mfma_f32_16x16x32_bf16 v[0:3], v[202:205], v[242:245], v[0:3]
	s_setprio 0
	s_barrier
	s_setprio 2
	s_add_i32 s57, 0, 0x18000
	v_add_u32_e32 v151, s57, v141
	s_add_i32 s58, 0, 0x1c000
	ds_read_b128 v[162:165], v151
	ds_read_b128 v[166:169], v151 offset:1024
	ds_read_b128 v[170:173], v151 offset:2048
	ds_read_b128 v[186:189], v151 offset:3072
	v_add_u32_e32 v151, s58, v141
	ds_read_b128 v[190:193], v151
	ds_read_b128 v[194:197], v151 offset:1024
	ds_read_b128 v[198:201], v151 offset:2048
	ds_read_b128 v[202:205], v151 offset:3072
	s_add_u32 s28, s28, 0x40000
	s_addc_u32 s29, s29, 0
	s_mov_b32 m0, s41
	v_lshl_add_u64 v[182:183], s[28:29], 0, v[134:135]
	ds_read_b128 v[206:209], v150 offset:32768
	ds_read_b128 v[210:213], v150 offset:33792
	ds_read_b128 v[214:217], v150 offset:34816
	ds_read_b128 v[218:221], v150 offset:35840
	ds_read_b128 v[222:225], v150 offset:36864
	ds_read_b128 v[226:229], v150 offset:37888
	ds_read_b128 v[230:233], v150 offset:38912
	ds_read_b128 v[242:245], v150 offset:39936
	global_load_lds_dwordx4 v[182:183], off
	v_lshl_add_u64 v[182:183], s[28:29], 0, v[132:133]
	s_mov_b32 m0, s42
	s_nop 0
	global_load_lds_dwordx4 v[182:183], off
	s_setprio 0
	s_waitcnt vmcnt(8) lgkmcnt(0)
	s_barrier
	s_setprio 1
	v_mfma_f32_16x16x32_bf16 v[126:129], v[162:165], v[206:209], v[126:129]
	v_mfma_f32_16x16x32_bf16 v[122:125], v[170:173], v[206:209], v[122:125]
	v_mfma_f32_16x16x32_bf16 v[118:121], v[162:165], v[214:217], v[118:121]
	v_mfma_f32_16x16x32_bf16 v[114:117], v[170:173], v[214:217], v[114:117]
	v_mfma_f32_16x16x32_bf16 v[110:113], v[162:165], v[222:225], v[110:113]
	v_mfma_f32_16x16x32_bf16 v[106:109], v[170:173], v[222:225], v[106:109]
	v_mfma_f32_16x16x32_bf16 v[102:105], v[162:165], v[230:233], v[102:105]
	v_mfma_f32_16x16x32_bf16 v[98:101], v[170:173], v[230:233], v[98:101]
	v_mfma_f32_16x16x32_bf16 v[126:129], v[166:169], v[210:213], v[126:129]
	v_mfma_f32_16x16x32_bf16 v[122:125], v[186:189], v[210:213], v[122:125]
	v_mfma_f32_16x16x32_bf16 v[118:121], v[166:169], v[218:221], v[118:121]
	v_mfma_f32_16x16x32_bf16 v[114:117], v[186:189], v[218:221], v[114:117]
	v_mfma_f32_16x16x32_bf16 v[110:113], v[166:169], v[226:229], v[110:113]
	v_mfma_f32_16x16x32_bf16 v[106:109], v[186:189], v[226:229], v[106:109]
	v_mfma_f32_16x16x32_bf16 v[102:105], v[166:169], v[242:245], v[102:105]
	v_mfma_f32_16x16x32_bf16 v[98:101], v[186:189], v[242:245], v[98:101]
	s_setprio 0
	s_setprio 1
	v_mfma_f32_16x16x32_bf16 v[68:71], v[190:193], v[206:209], v[68:71]
	v_mfma_f32_16x16x32_bf16 v[64:67], v[198:201], v[206:209], v[64:67]
	v_mfma_f32_16x16x32_bf16 v[52:55], v[190:193], v[214:217], v[52:55]
	v_mfma_f32_16x16x32_bf16 v[48:51], v[198:201], v[214:217], v[48:51]
	v_mfma_f32_16x16x32_bf16 v[44:47], v[190:193], v[222:225], v[44:47]
	v_mfma_f32_16x16x32_bf16 v[40:43], v[198:201], v[222:225], v[40:43]
	v_mfma_f32_16x16x32_bf16 v[36:39], v[190:193], v[230:233], v[36:39]
	v_mfma_f32_16x16x32_bf16 v[32:35], v[198:201], v[230:233], v[32:35]
	v_mfma_f32_16x16x32_bf16 v[68:71], v[194:197], v[210:213], v[68:71]
	v_mfma_f32_16x16x32_bf16 v[64:67], v[202:205], v[210:213], v[64:67]
	v_mfma_f32_16x16x32_bf16 v[52:55], v[194:197], v[218:221], v[52:55]
	v_mfma_f32_16x16x32_bf16 v[48:51], v[202:205], v[218:221], v[48:51]
	v_mfma_f32_16x16x32_bf16 v[44:47], v[194:197], v[226:229], v[44:47]
	v_mfma_f32_16x16x32_bf16 v[40:43], v[202:205], v[226:229], v[40:43]
	v_mfma_f32_16x16x32_bf16 v[36:39], v[194:197], v[242:245], v[36:39]
	v_mfma_f32_16x16x32_bf16 v[32:35], v[202:205], v[242:245], v[32:35]
	s_setprio 0
	s_barrier
	s_setprio 2
	s_add_i32 s28, s57, s36
	v_lshl_add_u64 v[152:153], v[152:153], 0, s[16:17]
	s_mov_b32 m0, s28
	ds_read_b128 v[206:209], v150 offset:49152
	ds_read_b128 v[210:213], v150 offset:50176
	ds_read_b128 v[214:217], v150 offset:51200
	ds_read_b128 v[218:221], v150 offset:52224
	ds_read_b128 v[222:225], v150 offset:53248
	ds_read_b128 v[226:229], v150 offset:54272
	ds_read_b128 v[230:233], v150 offset:55296
	ds_read_b128 v[242:245], v150 offset:56320
	global_load_lds_dwordx4 v[152:153], off
	s_add_i32 m0, s28, 0x2000
	s_add_u32 s26, s26, 0x40080
	v_lshl_add_u64 v[152:153], v[154:155], 0, s[16:17]
	s_addc_u32 s27, s27, 0
	s_add_i32 s28, s58, s36
	global_load_lds_dwordx4 v[152:153], off
	v_lshl_add_u64 v[152:153], s[26:27], 0, v[96:97]
	s_mov_b32 m0, s28
	s_nop 0
	global_load_lds_dwordx4 v[152:153], off
	v_lshl_add_u64 v[152:153], s[26:27], 0, v[130:131]
	s_add_i32 m0, s28, 0x2000
	s_nop 0
	global_load_lds_dwordx4 v[152:153], off
	v_lshl_add_u64 v[152:153], v[156:157], 0, s[16:17]
	s_mov_b32 m0, s45
	s_nop 0
	global_load_lds_dwordx4 v[152:153], off
	v_lshl_add_u64 v[152:153], v[158:159], 0, s[16:17]
	s_mov_b32 m0, s46
	s_nop 0
	global_load_lds_dwordx4 v[152:153], off
	s_setprio 0
	s_waitcnt vmcnt(8) lgkmcnt(0)
	s_barrier
	s_setprio 1
	v_mfma_f32_16x16x32_bf16 v[92:95], v[162:165], v[206:209], v[92:95]
	v_mfma_f32_16x16x32_bf16 v[88:91], v[170:173], v[206:209], v[88:91]
	v_mfma_f32_16x16x32_bf16 v[84:87], v[162:165], v[214:217], v[84:87]
	v_mfma_f32_16x16x32_bf16 v[80:83], v[170:173], v[214:217], v[80:83]
	v_mfma_f32_16x16x32_bf16 v[76:79], v[162:165], v[222:225], v[76:79]
	v_mfma_f32_16x16x32_bf16 v[72:75], v[170:173], v[222:225], v[72:75]
	v_mfma_f32_16x16x32_bf16 v[60:63], v[162:165], v[230:233], v[60:63]
	v_mfma_f32_16x16x32_bf16 v[56:59], v[170:173], v[230:233], v[56:59]
	v_mfma_f32_16x16x32_bf16 v[92:95], v[166:169], v[210:213], v[92:95]
	v_mfma_f32_16x16x32_bf16 v[88:91], v[186:189], v[210:213], v[88:91]
	v_mfma_f32_16x16x32_bf16 v[84:87], v[166:169], v[218:221], v[84:87]
	v_mfma_f32_16x16x32_bf16 v[80:83], v[186:189], v[218:221], v[80:83]
	v_mfma_f32_16x16x32_bf16 v[76:79], v[166:169], v[226:229], v[76:79]
	v_mfma_f32_16x16x32_bf16 v[72:75], v[186:189], v[226:229], v[72:75]
	v_mfma_f32_16x16x32_bf16 v[60:63], v[166:169], v[242:245], v[60:63]
	v_mfma_f32_16x16x32_bf16 v[56:59], v[186:189], v[242:245], v[56:59]
	s_setprio 0
	s_setprio 1
	v_mfma_f32_16x16x32_bf16 v[28:31], v[190:193], v[206:209], v[28:31]
	v_mfma_f32_16x16x32_bf16 v[24:27], v[198:201], v[206:209], v[24:27]
	v_mfma_f32_16x16x32_bf16 v[20:23], v[190:193], v[214:217], v[20:23]
	v_mfma_f32_16x16x32_bf16 v[16:19], v[198:201], v[214:217], v[16:19]
	v_mfma_f32_16x16x32_bf16 v[12:15], v[190:193], v[222:225], v[12:15]
	v_mfma_f32_16x16x32_bf16 v[8:11], v[198:201], v[222:225], v[8:11]
	v_mfma_f32_16x16x32_bf16 v[4:7], v[190:193], v[230:233], v[4:7]
	v_mfma_f32_16x16x32_bf16 v[0:3], v[198:201], v[230:233], v[0:3]
	v_mfma_f32_16x16x32_bf16 v[28:31], v[194:197], v[210:213], v[28:31]
	v_mfma_f32_16x16x32_bf16 v[24:27], v[202:205], v[210:213], v[24:27]
	v_mfma_f32_16x16x32_bf16 v[20:23], v[194:197], v[218:221], v[20:23]
	v_mfma_f32_16x16x32_bf16 v[16:19], v[202:205], v[218:221], v[16:19]
	v_mfma_f32_16x16x32_bf16 v[12:15], v[194:197], v[226:229], v[12:15]
	v_mfma_f32_16x16x32_bf16 v[8:11], v[202:205], v[226:229], v[8:11]
	v_mfma_f32_16x16x32_bf16 v[4:7], v[194:197], v[242:245], v[4:7]
	v_mfma_f32_16x16x32_bf16 v[0:3], v[202:205], v[242:245], v[0:3]
	s_setprio 0
	s_barrier
	s_setprio 2
	s_add_i32 s56, s56, 2
	s_add_u32 s14, s14, 0x100
	s_addc_u32 s15, s15, 0
	s_add_u32 s54, s54, 0x100
	s_addc_u32 s55, s55, 0
	s_cmp_gt_u32 s56, 13
	s_cbranch_scc0 .LBB0_393
	s_and_b64 vcc, exec, s[12:13]
	s_cbranch_vccz .LBB0_396
	s_barrier

.LBB0_427:
	s_add_u32 s14, s4, 0xfffc0080
	s_addc_u32 s15, s5, -1
	s_add_i32 s62, 0, 0x10000
	s_cmp_eq_u32 s61, 12
	s_cselect_b32 s37, s29, s15
	s_cselect_b32 s36, s57, s14
	v_add_u32_e32 v154, s62, v169
	s_cselect_b32 s15, s27, s60
	s_cselect_b32 s14, s58, s59
	s_add_i32 s64, 0, 0x14000
	ds_read_b128 v[142:145], v154
	ds_read_b128 v[146:149], v154 offset:1024
	ds_read_b128 v[150:153], v154 offset:2048
	ds_read_b128 v[162:165], v154 offset:3072
	v_add_u32_e32 v154, s64, v169
	ds_read_b128 v[186:189], v154
	ds_read_b128 v[190:193], v154 offset:1024
	ds_read_b128 v[194:197], v154 offset:2048
	ds_read_b128 v[198:201], v154 offset:3072
	v_lshl_add_u64 v[154:155], s[4:5], 0, v[138:139]
	s_add_i32 m0, s43, 0xc000
	ds_read_b128 v[202:205], v173
	ds_read_b128 v[206:209], v173 offset:1024
	ds_read_b128 v[210:213], v173 offset:2048
	ds_read_b128 v[214:217], v173 offset:3072
	ds_read_b128 v[218:221], v173 offset:4096
	ds_read_b128 v[222:225], v173 offset:5120
	ds_read_b128 v[226:229], v173 offset:6144
	ds_read_b128 v[230:233], v173 offset:7168
	global_load_lds_dwordx4 v[154:155], off
	v_lshl_add_u64 v[154:155], s[4:5], 0, v[140:141]
	s_add_i32 m0, s43, 0xe000
	s_nop 0
	global_load_lds_dwordx4 v[154:155], off
	s_setprio 0
	s_waitcnt vmcnt(8) lgkmcnt(0)
	s_barrier
	s_setprio 1
	v_mfma_f32_16x16x32_bf16 v[126:129], v[142:145], v[202:205], v[126:129]
	v_mfma_f32_16x16x32_bf16 v[122:125], v[150:153], v[202:205], v[122:125]
	v_mfma_f32_16x16x32_bf16 v[110:113], v[142:145], v[210:213], v[110:113]
	v_mfma_f32_16x16x32_bf16 v[106:109], v[150:153], v[210:213], v[106:109]
	v_mfma_f32_16x16x32_bf16 v[92:95], v[142:145], v[218:221], v[92:95]
	v_mfma_f32_16x16x32_bf16 v[88:91], v[150:153], v[218:221], v[88:91]
	v_mfma_f32_16x16x32_bf16 v[76:79], v[142:145], v[226:229], v[76:79]
	v_mfma_f32_16x16x32_bf16 v[72:75], v[150:153], v[226:229], v[72:75]
	v_mfma_f32_16x16x32_bf16 v[126:129], v[146:149], v[206:209], v[126:129]
	v_mfma_f32_16x16x32_bf16 v[122:125], v[162:165], v[206:209], v[122:125]
	v_mfma_f32_16x16x32_bf16 v[110:113], v[146:149], v[214:217], v[110:113]
	v_mfma_f32_16x16x32_bf16 v[106:109], v[162:165], v[214:217], v[106:109]
	v_mfma_f32_16x16x32_bf16 v[92:95], v[146:149], v[222:225], v[92:95]
	v_mfma_f32_16x16x32_bf16 v[88:91], v[162:165], v[222:225], v[88:91]
	v_mfma_f32_16x16x32_bf16 v[76:79], v[146:149], v[230:233], v[76:79]
	v_mfma_f32_16x16x32_bf16 v[72:75], v[162:165], v[230:233], v[72:75]
	s_setprio 0
	s_setprio 1
	v_mfma_f32_16x16x32_bf16 v[118:121], v[186:189], v[202:205], v[118:121]
	v_mfma_f32_16x16x32_bf16 v[114:117], v[194:197], v[202:205], v[114:117]
	v_mfma_f32_16x16x32_bf16 v[102:105], v[186:189], v[210:213], v[102:105]
	v_mfma_f32_16x16x32_bf16 v[98:101], v[194:197], v[210:213], v[98:101]
	v_mfma_f32_16x16x32_bf16 v[84:87], v[186:189], v[218:221], v[84:87]
	v_mfma_f32_16x16x32_bf16 v[80:83], v[194:197], v[218:221], v[80:83]
	v_mfma_f32_16x16x32_bf16 v[68:71], v[186:189], v[226:229], v[68:71]
	v_mfma_f32_16x16x32_bf16 v[64:67], v[194:197], v[226:229], v[64:67]
	v_mfma_f32_16x16x32_bf16 v[118:121], v[190:193], v[206:209], v[118:121]
	v_mfma_f32_16x16x32_bf16 v[114:117], v[198:201], v[206:209], v[114:117]
	v_mfma_f32_16x16x32_bf16 v[102:105], v[190:193], v[214:217], v[102:105]
	v_mfma_f32_16x16x32_bf16 v[98:101], v[198:201], v[214:217], v[98:101]
	v_mfma_f32_16x16x32_bf16 v[84:87], v[190:193], v[222:225], v[84:87]
	v_mfma_f32_16x16x32_bf16 v[80:83], v[198:201], v[222:225], v[80:83]
	v_mfma_f32_16x16x32_bf16 v[68:71], v[190:193], v[230:233], v[68:71]
	v_mfma_f32_16x16x32_bf16 v[64:67], v[198:201], v[230:233], v[64:67]
	s_setprio 0
	s_barrier
	s_setprio 2
	s_add_i32 s62, s62, s42
	v_lshl_add_u64 v[154:155], s[14:15], 0, v[96:97]
	s_mov_b32 m0, s62
	ds_read_b128 v[202:205], v173 offset:16384
	ds_read_b128 v[206:209], v173 offset:17408
	ds_read_b128 v[210:213], v173 offset:18432
	ds_read_b128 v[214:217], v173 offset:19456
	ds_read_b128 v[218:221], v173 offset:20480
	ds_read_b128 v[222:225], v173 offset:21504
	ds_read_b128 v[226:229], v173 offset:22528
	ds_read_b128 v[230:233], v173 offset:23552
	global_load_lds_dwordx4 v[154:155], off
	s_add_i32 m0, s62, 0x2000
	s_add_u32 s62, s14, 0x40000
	v_lshl_add_u64 v[156:157], s[14:15], 0, v[130:131]
	s_addc_u32 s63, s15, 0
	s_add_i32 s64, s64, s42
	global_load_lds_dwordx4 v[156:157], off
	v_lshl_add_u64 v[158:159], s[62:63], 0, v[96:97]
	s_mov_b32 m0, s64
	v_lshl_add_u64 v[166:167], s[36:37], 0, v[132:133]
	global_load_lds_dwordx4 v[158:159], off
	v_lshl_add_u64 v[158:159], s[62:63], 0, v[130:131]
	s_add_i32 m0, s64, 0x2000
	s_nop 0
	global_load_lds_dwordx4 v[158:159], off
	v_lshl_add_u64 v[158:159], s[36:37], 0, v[134:135]
	s_mov_b32 m0, s43
	s_nop 0
	global_load_lds_dwordx4 v[158:159], off
	s_mov_b32 m0, s44
	s_nop 0
	global_load_lds_dwordx4 v[166:167], off
	s_setprio 0
	s_waitcnt vmcnt(8) lgkmcnt(0)
	s_barrier
	s_setprio 1
	v_mfma_f32_16x16x32_bf16 v[60:63], v[142:145], v[202:205], v[60:63]
	v_mfma_f32_16x16x32_bf16 v[56:59], v[150:153], v[202:205], v[56:59]
	v_mfma_f32_16x16x32_bf16 v[44:47], v[142:145], v[210:213], v[44:47]
	v_mfma_f32_16x16x32_bf16 v[40:43], v[150:153], v[210:213], v[40:43]
	v_mfma_f32_16x16x32_bf16 v[28:31], v[142:145], v[218:221], v[28:31]
	v_mfma_f32_16x16x32_bf16 v[24:27], v[150:153], v[218:221], v[24:27]
	v_mfma_f32_16x16x32_bf16 v[12:15], v[142:145], v[226:229], v[12:15]
	v_mfma_f32_16x16x32_bf16 v[8:11], v[150:153], v[226:229], v[8:11]
	v_mfma_f32_16x16x32_bf16 v[60:63], v[146:149], v[206:209], v[60:63]
	v_mfma_f32_16x16x32_bf16 v[56:59], v[162:165], v[206:209], v[56:59]
	v_mfma_f32_16x16x32_bf16 v[44:47], v[146:149], v[214:217], v[44:47]
	v_mfma_f32_16x16x32_bf16 v[40:43], v[162:165], v[214:217], v[40:43]
	v_mfma_f32_16x16x32_bf16 v[28:31], v[146:149], v[222:225], v[28:31]
	v_mfma_f32_16x16x32_bf16 v[24:27], v[162:165], v[222:225], v[24:27]
	v_mfma_f32_16x16x32_bf16 v[12:15], v[146:149], v[230:233], v[12:15]
	v_mfma_f32_16x16x32_bf16 v[8:11], v[162:165], v[230:233], v[8:11]
	s_setprio 0
	s_setprio 1
	v_mfma_f32_16x16x32_bf16 v[52:55], v[186:189], v[202:205], v[52:55]
	v_mfma_f32_16x16x32_bf16 v[48:51], v[194:197], v[202:205], v[48:51]
	v_mfma_f32_16x16x32_bf16 v[36:39], v[186:189], v[210:213], v[36:39]
	v_mfma_f32_16x16x32_bf16 v[32:35], v[194:197], v[210:213], v[32:35]
	v_mfma_f32_16x16x32_bf16 v[20:23], v[186:189], v[218:221], v[20:23]
	v_mfma_f32_16x16x32_bf16 v[16:19], v[194:197], v[218:221], v[16:19]
	v_mfma_f32_16x16x32_bf16 v[4:7], v[186:189], v[226:229], v[4:7]
	v_mfma_f32_16x16x32_bf16 v[0:3], v[194:197], v[226:229], v[0:3]
	v_mfma_f32_16x16x32_bf16 v[52:55], v[190:193], v[206:209], v[52:55]
	v_mfma_f32_16x16x32_bf16 v[48:51], v[198:201], v[206:209], v[48:51]
	v_mfma_f32_16x16x32_bf16 v[36:39], v[190:193], v[214:217], v[36:39]
	v_mfma_f32_16x16x32_bf16 v[32:35], v[198:201], v[214:217], v[32:35]
	v_mfma_f32_16x16x32_bf16 v[20:23], v[190:193], v[222:225], v[20:23]
	v_mfma_f32_16x16x32_bf16 v[16:19], v[198:201], v[222:225], v[16:19]
	v_mfma_f32_16x16x32_bf16 v[4:7], v[190:193], v[230:233], v[4:7]
	v_mfma_f32_16x16x32_bf16 v[0:3], v[198:201], v[230:233], v[0:3]
	s_setprio 0
	s_barrier
	s_setprio 2
	s_add_i32 s62, 0, 0x18000
	s_add_i32 s63, 0, 0x1c000
	v_add_u32_e32 v162, s62, v169
	v_add_u32_e32 v182, s63, v169
	ds_read_b128 v[142:145], v162
	ds_read_b128 v[146:149], v162 offset:1024
	ds_read_b128 v[150:153], v162 offset:2048
	ds_read_b128 v[162:165], v162 offset:3072
	ds_read_b128 v[186:189], v182
	ds_read_b128 v[190:193], v182 offset:1024
	ds_read_b128 v[194:197], v182 offset:2048
	ds_read_b128 v[198:201], v182 offset:3072
	s_add_u32 s36, s36, 0x40000
	s_addc_u32 s37, s37, 0
	s_mov_b32 m0, s45
	v_lshl_add_u64 v[182:183], s[36:37], 0, v[134:135]
	ds_read_b128 v[202:205], v173 offset:32768
	ds_read_b128 v[206:209], v173 offset:33792
	ds_read_b128 v[210:213], v173 offset:34816
	ds_read_b128 v[214:217], v173 offset:35840
	ds_read_b128 v[218:221], v173 offset:36864
	ds_read_b128 v[222:225], v173 offset:37888
	ds_read_b128 v[226:229], v173 offset:38912
	ds_read_b128 v[230:233], v173 offset:39936
	global_load_lds_dwordx4 v[182:183], off
	v_lshl_add_u64 v[182:183], s[36:37], 0, v[132:133]
	s_mov_b32 m0, s46
	s_nop 0
	global_load_lds_dwordx4 v[182:183], off
	s_setprio 0
	s_waitcnt vmcnt(8) lgkmcnt(0)
	s_barrier
	s_setprio 1
	v_mfma_f32_16x16x32_bf16 v[126:129], v[142:145], v[202:205], v[126:129]
	v_mfma_f32_16x16x32_bf16 v[122:125], v[150:153], v[202:205], v[122:125]
	v_mfma_f32_16x16x32_bf16 v[110:113], v[142:145], v[210:213], v[110:113]
	v_mfma_f32_16x16x32_bf16 v[106:109], v[150:153], v[210:213], v[106:109]
	v_mfma_f32_16x16x32_bf16 v[92:95], v[142:145], v[218:221], v[92:95]
	v_mfma_f32_16x16x32_bf16 v[88:91], v[150:153], v[218:221], v[88:91]
	v_mfma_f32_16x16x32_bf16 v[76:79], v[142:145], v[226:229], v[76:79]
	v_mfma_f32_16x16x32_bf16 v[72:75], v[150:153], v[226:229], v[72:75]
	v_mfma_f32_16x16x32_bf16 v[126:129], v[146:149], v[206:209], v[126:129]
	v_mfma_f32_16x16x32_bf16 v[122:125], v[162:165], v[206:209], v[122:125]
	v_mfma_f32_16x16x32_bf16 v[110:113], v[146:149], v[214:217], v[110:113]
	v_mfma_f32_16x16x32_bf16 v[106:109], v[162:165], v[214:217], v[106:109]
	v_mfma_f32_16x16x32_bf16 v[92:95], v[146:149], v[222:225], v[92:95]
	v_mfma_f32_16x16x32_bf16 v[88:91], v[162:165], v[222:225], v[88:91]
	v_mfma_f32_16x16x32_bf16 v[76:79], v[146:149], v[230:233], v[76:79]
	v_mfma_f32_16x16x32_bf16 v[72:75], v[162:165], v[230:233], v[72:75]
	s_setprio 0
	s_setprio 1
	v_mfma_f32_16x16x32_bf16 v[118:121], v[186:189], v[202:205], v[118:121]
	v_mfma_f32_16x16x32_bf16 v[114:117], v[194:197], v[202:205], v[114:117]
	v_mfma_f32_16x16x32_bf16 v[102:105], v[186:189], v[210:213], v[102:105]
	v_mfma_f32_16x16x32_bf16 v[98:101], v[194:197], v[210:213], v[98:101]
	v_mfma_f32_16x16x32_bf16 v[84:87], v[186:189], v[218:221], v[84:87]
	v_mfma_f32_16x16x32_bf16 v[80:83], v[194:197], v[218:221], v[80:83]
	v_mfma_f32_16x16x32_bf16 v[68:71], v[186:189], v[226:229], v[68:71]
	v_mfma_f32_16x16x32_bf16 v[64:67], v[194:197], v[226:229], v[64:67]
	v_mfma_f32_16x16x32_bf16 v[118:121], v[190:193], v[206:209], v[118:121]
	v_mfma_f32_16x16x32_bf16 v[114:117], v[198:201], v[206:209], v[114:117]
	v_mfma_f32_16x16x32_bf16 v[102:105], v[190:193], v[214:217], v[102:105]
	v_mfma_f32_16x16x32_bf16 v[98:101], v[198:201], v[214:217], v[98:101]
	v_mfma_f32_16x16x32_bf16 v[84:87], v[190:193], v[222:225], v[84:87]
	v_mfma_f32_16x16x32_bf16 v[80:83], v[198:201], v[222:225], v[80:83]
	v_mfma_f32_16x16x32_bf16 v[68:71], v[190:193], v[230:233], v[68:71]
	v_mfma_f32_16x16x32_bf16 v[64:67], v[198:201], v[230:233], v[64:67]
	s_setprio 0
	s_barrier
	s_setprio 2
	s_add_i32 s36, s62, s42
	v_lshl_add_u64 v[154:155], v[154:155], 0, s[16:17]
	s_mov_b32 m0, s36
	ds_read_b128 v[202:205], v173 offset:49152
	ds_read_b128 v[206:209], v173 offset:50176
	ds_read_b128 v[210:213], v173 offset:51200
	ds_read_b128 v[214:217], v173 offset:52224
	ds_read_b128 v[218:221], v173 offset:53248
	ds_read_b128 v[222:225], v173 offset:54272
	ds_read_b128 v[226:229], v173 offset:55296
	ds_read_b128 v[230:233], v173 offset:56320
	global_load_lds_dwordx4 v[154:155], off
	s_add_i32 m0, s36, 0x2000
	s_add_u32 s14, s14, 0x40080
	v_lshl_add_u64 v[154:155], v[156:157], 0, s[16:17]
	s_addc_u32 s15, s15, 0
	s_add_i32 s36, s63, s42
	global_load_lds_dwordx4 v[154:155], off
	v_lshl_add_u64 v[154:155], s[14:15], 0, v[96:97]
	s_mov_b32 m0, s36
	s_nop 0
	global_load_lds_dwordx4 v[154:155], off
	v_lshl_add_u64 v[154:155], s[14:15], 0, v[130:131]
	s_add_i32 m0, s36, 0x2000
	s_nop 0
	global_load_lds_dwordx4 v[154:155], off
	v_lshl_add_u64 v[154:155], v[158:159], 0, s[16:17]
	s_mov_b32 m0, s52
	s_nop 0
	global_load_lds_dwordx4 v[154:155], off
	v_lshl_add_u64 v[154:155], v[166:167], 0, s[16:17]
	s_mov_b32 m0, s53
	s_nop 0
	global_load_lds_dwordx4 v[154:155], off
	s_setprio 0
	s_waitcnt vmcnt(8) lgkmcnt(0)
	s_barrier
	s_setprio 1
	v_mfma_f32_16x16x32_bf16 v[60:63], v[142:145], v[202:205], v[60:63]
	v_mfma_f32_16x16x32_bf16 v[56:59], v[150:153], v[202:205], v[56:59]
	v_mfma_f32_16x16x32_bf16 v[44:47], v[142:145], v[210:213], v[44:47]
	v_mfma_f32_16x16x32_bf16 v[40:43], v[150:153], v[210:213], v[40:43]
	v_mfma_f32_16x16x32_bf16 v[28:31], v[142:145], v[218:221], v[28:31]
	v_mfma_f32_16x16x32_bf16 v[24:27], v[150:153], v[218:221], v[24:27]
	v_mfma_f32_16x16x32_bf16 v[12:15], v[142:145], v[226:229], v[12:15]
	v_mfma_f32_16x16x32_bf16 v[8:11], v[150:153], v[226:229], v[8:11]
	v_mfma_f32_16x16x32_bf16 v[60:63], v[146:149], v[206:209], v[60:63]
	v_mfma_f32_16x16x32_bf16 v[56:59], v[162:165], v[206:209], v[56:59]
	v_mfma_f32_16x16x32_bf16 v[44:47], v[146:149], v[214:217], v[44:47]
	v_mfma_f32_16x16x32_bf16 v[40:43], v[162:165], v[214:217], v[40:43]
	v_mfma_f32_16x16x32_bf16 v[28:31], v[146:149], v[222:225], v[28:31]
	v_mfma_f32_16x16x32_bf16 v[24:27], v[162:165], v[222:225], v[24:27]
	v_mfma_f32_16x16x32_bf16 v[12:15], v[146:149], v[230:233], v[12:15]
	v_mfma_f32_16x16x32_bf16 v[8:11], v[162:165], v[230:233], v[8:11]
	s_setprio 0
	s_setprio 1
	v_mfma_f32_16x16x32_bf16 v[52:55], v[186:189], v[202:205], v[52:55]
	v_mfma_f32_16x16x32_bf16 v[48:51], v[194:197], v[202:205], v[48:51]
	v_mfma_f32_16x16x32_bf16 v[36:39], v[186:189], v[210:213], v[36:39]
	v_mfma_f32_16x16x32_bf16 v[32:35], v[194:197], v[210:213], v[32:35]
	v_mfma_f32_16x16x32_bf16 v[20:23], v[186:189], v[218:221], v[20:23]
	v_mfma_f32_16x16x32_bf16 v[16:19], v[194:197], v[218:221], v[16:19]
	v_mfma_f32_16x16x32_bf16 v[4:7], v[186:189], v[226:229], v[4:7]
	v_mfma_f32_16x16x32_bf16 v[0:3], v[194:197], v[226:229], v[0:3]
	v_mfma_f32_16x16x32_bf16 v[52:55], v[190:193], v[206:209], v[52:55]
	v_mfma_f32_16x16x32_bf16 v[48:51], v[198:201], v[206:209], v[48:51]
	v_mfma_f32_16x16x32_bf16 v[36:39], v[190:193], v[214:217], v[36:39]
	v_mfma_f32_16x16x32_bf16 v[32:35], v[198:201], v[214:217], v[32:35]
	v_mfma_f32_16x16x32_bf16 v[20:23], v[190:193], v[222:225], v[20:23]
	v_mfma_f32_16x16x32_bf16 v[16:19], v[198:201], v[222:225], v[16:19]
	v_mfma_f32_16x16x32_bf16 v[4:7], v[190:193], v[230:233], v[4:7]
	v_mfma_f32_16x16x32_bf16 v[0:3], v[198:201], v[230:233], v[0:3]
	s_setprio 0
	s_barrier
	s_setprio 2
	s_add_i32 s61, s61, 2
	s_add_u32 s4, s4, 0x100
	s_addc_u32 s5, s5, 0
	s_add_u32 s59, s59, 0x100
	s_addc_u32 s60, s60, 0
	s_cmp_gt_u32 s61, 13
	s_cbranch_scc0 .LBB0_427
	s_and_b64 vcc, exec, s[24:25]
	s_cbranch_vccz .LBB0_430
	s_barrier

.LBB0_449:
	s_add_u32 s30, s14, 0xfffc0080
	s_addc_u32 s31, s15, -1
	s_add_i32 s60, 0, 0x10000
	s_cmp_eq_u32 s59, 12
	s_cselect_b32 s35, s25, s31
	s_cselect_b32 s34, s55, s30
	v_add_u32_e32 v96, s60, v151
	s_cselect_b32 s31, s13, s58
	s_cselect_b32 s30, s56, s57
	s_add_i32 s62, 0, 0x14000
	ds_read_b128 v[144:147], v96
	ds_read_b128 v[164:167], v96 offset:1024
	ds_read_b128 v[168:171], v96 offset:2048
	ds_read_b128 v[186:189], v96 offset:3072
	v_add_u32_e32 v96, s62, v151
	ds_read_b128 v[190:193], v96
	ds_read_b128 v[194:197], v96 offset:1024
	ds_read_b128 v[198:201], v96 offset:2048
	ds_read_b128 v[202:205], v96 offset:3072
	v_lshl_add_u64 v[148:149], s[14:15], 0, v[140:141]
	s_add_i32 m0, s41, 0xc000
	ds_read_b128 v[206:209], v163
	ds_read_b128 v[210:213], v163 offset:1024
	ds_read_b128 v[214:217], v163 offset:2048
	ds_read_b128 v[218:221], v163 offset:3072
	ds_read_b128 v[222:225], v163 offset:4096
	ds_read_b128 v[226:229], v163 offset:5120
	ds_read_b128 v[230:233], v163 offset:6144
	ds_read_b128 v[242:245], v163 offset:7168
	global_load_lds_dwordx4 v[148:149], off
	v_lshl_add_u64 v[148:149], s[14:15], 0, v[142:143]
	s_add_i32 m0, s41, 0xe000
	s_nop 0
	global_load_lds_dwordx4 v[148:149], off
	s_setprio 0
	s_waitcnt vmcnt(8) lgkmcnt(0)
	s_barrier
	s_setprio 1
	v_mfma_f32_16x16x32_bf16 v[126:129], v[144:147], v[206:209], v[126:129]
	v_mfma_f32_16x16x32_bf16 v[122:125], v[168:171], v[206:209], v[122:125]
	v_mfma_f32_16x16x32_bf16 v[110:113], v[144:147], v[214:217], v[110:113]
	v_mfma_f32_16x16x32_bf16 v[106:109], v[168:171], v[214:217], v[106:109]
	v_mfma_f32_16x16x32_bf16 v[92:95], v[144:147], v[222:225], v[92:95]
	v_mfma_f32_16x16x32_bf16 v[88:91], v[168:171], v[222:225], v[88:91]
	v_mfma_f32_16x16x32_bf16 v[76:79], v[144:147], v[230:233], v[76:79]
	v_mfma_f32_16x16x32_bf16 v[72:75], v[168:171], v[230:233], v[72:75]
	v_mfma_f32_16x16x32_bf16 v[126:129], v[164:167], v[210:213], v[126:129]
	v_mfma_f32_16x16x32_bf16 v[122:125], v[186:189], v[210:213], v[122:125]
	v_mfma_f32_16x16x32_bf16 v[110:113], v[164:167], v[218:221], v[110:113]
	v_mfma_f32_16x16x32_bf16 v[106:109], v[186:189], v[218:221], v[106:109]
	v_mfma_f32_16x16x32_bf16 v[92:95], v[164:167], v[226:229], v[92:95]
	v_mfma_f32_16x16x32_bf16 v[88:91], v[186:189], v[226:229], v[88:91]
	v_mfma_f32_16x16x32_bf16 v[76:79], v[164:167], v[242:245], v[76:79]
	v_mfma_f32_16x16x32_bf16 v[72:75], v[186:189], v[242:245], v[72:75]
	s_setprio 0
	s_setprio 1
	v_mfma_f32_16x16x32_bf16 v[118:121], v[190:193], v[206:209], v[118:121]
	v_mfma_f32_16x16x32_bf16 v[114:117], v[198:201], v[206:209], v[114:117]
	v_mfma_f32_16x16x32_bf16 v[102:105], v[190:193], v[214:217], v[102:105]
	v_mfma_f32_16x16x32_bf16 v[98:101], v[198:201], v[214:217], v[98:101]
	v_mfma_f32_16x16x32_bf16 v[84:87], v[190:193], v[222:225], v[84:87]
	v_mfma_f32_16x16x32_bf16 v[80:83], v[198:201], v[222:225], v[80:83]
	v_mfma_f32_16x16x32_bf16 v[68:71], v[190:193], v[230:233], v[68:71]
	v_mfma_f32_16x16x32_bf16 v[64:67], v[198:201], v[230:233], v[64:67]
	v_mfma_f32_16x16x32_bf16 v[118:121], v[194:197], v[210:213], v[118:121]
	v_mfma_f32_16x16x32_bf16 v[114:117], v[202:205], v[210:213], v[114:117]
	v_mfma_f32_16x16x32_bf16 v[102:105], v[194:197], v[218:221], v[102:105]
	v_mfma_f32_16x16x32_bf16 v[98:101], v[202:205], v[218:221], v[98:101]
	v_mfma_f32_16x16x32_bf16 v[84:87], v[194:197], v[226:229], v[84:87]
	v_mfma_f32_16x16x32_bf16 v[80:83], v[202:205], v[226:229], v[80:83]
	v_mfma_f32_16x16x32_bf16 v[68:71], v[194:197], v[242:245], v[68:71]
	v_mfma_f32_16x16x32_bf16 v[64:67], v[202:205], v[242:245], v[64:67]
	s_setprio 0
	s_barrier
	s_setprio 2
	s_add_i32 s60, s60, s40
	v_lshl_add_u64 v[148:149], s[30:31], 0, v[134:135]
	s_mov_b32 m0, s60
	ds_read_b128 v[206:209], v163 offset:16384
	ds_read_b128 v[210:213], v163 offset:17408
	ds_read_b128 v[214:217], v163 offset:18432
	ds_read_b128 v[218:221], v163 offset:19456
	ds_read_b128 v[222:225], v163 offset:20480
	ds_read_b128 v[226:229], v163 offset:21504
	ds_read_b128 v[230:233], v163 offset:22528
	ds_read_b128 v[242:245], v163 offset:23552
	global_load_lds_dwordx4 v[148:149], off
	s_add_i32 m0, s60, 0x2000
	s_add_u32 s60, s30, 0x40000
	v_lshl_add_u64 v[154:155], s[30:31], 0, v[130:131]
	s_addc_u32 s61, s31, 0
	s_add_i32 s62, s62, s40
	global_load_lds_dwordx4 v[154:155], off
	v_lshl_add_u64 v[156:157], s[60:61], 0, v[134:135]
	s_mov_b32 m0, s62
	v_lshl_add_u64 v[158:159], s[34:35], 0, v[132:133]
	global_load_lds_dwordx4 v[156:157], off
	v_lshl_add_u64 v[156:157], s[60:61], 0, v[130:131]
	s_add_i32 m0, s62, 0x2000
	s_nop 0
	global_load_lds_dwordx4 v[156:157], off
	v_lshl_add_u64 v[156:157], s[34:35], 0, v[136:137]
	s_mov_b32 m0, s41
	s_nop 0
	global_load_lds_dwordx4 v[156:157], off
	s_mov_b32 m0, s42
	s_nop 0
	global_load_lds_dwordx4 v[158:159], off
	s_setprio 0
	s_waitcnt vmcnt(8) lgkmcnt(0)
	s_barrier
	s_setprio 1
	v_mfma_f32_16x16x32_bf16 v[60:63], v[144:147], v[206:209], v[60:63]
	v_mfma_f32_16x16x32_bf16 v[56:59], v[168:171], v[206:209], v[56:59]
	v_mfma_f32_16x16x32_bf16 v[44:47], v[144:147], v[214:217], v[44:47]
	v_mfma_f32_16x16x32_bf16 v[40:43], v[168:171], v[214:217], v[40:43]
	v_mfma_f32_16x16x32_bf16 v[28:31], v[144:147], v[222:225], v[28:31]
	v_mfma_f32_16x16x32_bf16 v[24:27], v[168:171], v[222:225], v[24:27]
	v_mfma_f32_16x16x32_bf16 v[12:15], v[144:147], v[230:233], v[12:15]
	v_mfma_f32_16x16x32_bf16 v[8:11], v[168:171], v[230:233], v[8:11]
	v_mfma_f32_16x16x32_bf16 v[60:63], v[164:167], v[210:213], v[60:63]
	v_mfma_f32_16x16x32_bf16 v[56:59], v[186:189], v[210:213], v[56:59]
	v_mfma_f32_16x16x32_bf16 v[44:47], v[164:167], v[218:221], v[44:47]
	v_mfma_f32_16x16x32_bf16 v[40:43], v[186:189], v[218:221], v[40:43]
	v_mfma_f32_16x16x32_bf16 v[28:31], v[164:167], v[226:229], v[28:31]
	v_mfma_f32_16x16x32_bf16 v[24:27], v[186:189], v[226:229], v[24:27]
	v_mfma_f32_16x16x32_bf16 v[12:15], v[164:167], v[242:245], v[12:15]
	v_mfma_f32_16x16x32_bf16 v[8:11], v[186:189], v[242:245], v[8:11]
	s_setprio 0
	s_setprio 1
	v_mfma_f32_16x16x32_bf16 v[52:55], v[190:193], v[206:209], v[52:55]
	v_mfma_f32_16x16x32_bf16 v[48:51], v[198:201], v[206:209], v[48:51]
	v_mfma_f32_16x16x32_bf16 v[36:39], v[190:193], v[214:217], v[36:39]
	v_mfma_f32_16x16x32_bf16 v[32:35], v[198:201], v[214:217], v[32:35]
	v_mfma_f32_16x16x32_bf16 v[20:23], v[190:193], v[222:225], v[20:23]
	v_mfma_f32_16x16x32_bf16 v[16:19], v[198:201], v[222:225], v[16:19]
	v_mfma_f32_16x16x32_bf16 v[4:7], v[190:193], v[230:233], v[4:7]
	v_mfma_f32_16x16x32_bf16 v[0:3], v[198:201], v[230:233], v[0:3]
	v_mfma_f32_16x16x32_bf16 v[52:55], v[194:197], v[210:213], v[52:55]
	v_mfma_f32_16x16x32_bf16 v[48:51], v[202:205], v[210:213], v[48:51]
	v_mfma_f32_16x16x32_bf16 v[36:39], v[194:197], v[218:221], v[36:39]
	v_mfma_f32_16x16x32_bf16 v[32:35], v[202:205], v[218:221], v[32:35]
	v_mfma_f32_16x16x32_bf16 v[20:23], v[194:197], v[226:229], v[20:23]
	v_mfma_f32_16x16x32_bf16 v[16:19], v[202:205], v[226:229], v[16:19]
	v_mfma_f32_16x16x32_bf16 v[4:7], v[194:197], v[242:245], v[4:7]
	v_mfma_f32_16x16x32_bf16 v[0:3], v[202:205], v[242:245], v[0:3]
	s_setprio 0
	s_barrier
	s_setprio 2
	s_add_i32 s60, 0, 0x18000
	v_add_u32_e32 v96, s60, v151
	s_add_i32 s61, 0, 0x1c000
	ds_read_b128 v[144:147], v96
	ds_read_b128 v[164:167], v96 offset:1024
	ds_read_b128 v[168:171], v96 offset:2048
	ds_read_b128 v[186:189], v96 offset:3072
	v_add_u32_e32 v96, s61, v151
	ds_read_b128 v[190:193], v96
	ds_read_b128 v[194:197], v96 offset:1024
	ds_read_b128 v[198:201], v96 offset:2048
	ds_read_b128 v[202:205], v96 offset:3072
	s_add_u32 s34, s34, 0x40000
	s_addc_u32 s35, s35, 0
	s_mov_b32 m0, s43
	v_lshl_add_u64 v[172:173], s[34:35], 0, v[136:137]
	ds_read_b128 v[206:209], v163 offset:32768
	ds_read_b128 v[210:213], v163 offset:33792
	ds_read_b128 v[214:217], v163 offset:34816
	ds_read_b128 v[218:221], v163 offset:35840
	ds_read_b128 v[222:225], v163 offset:36864
	ds_read_b128 v[226:229], v163 offset:37888
	ds_read_b128 v[230:233], v163 offset:38912
	ds_read_b128 v[242:245], v163 offset:39936
	global_load_lds_dwordx4 v[172:173], off
	v_lshl_add_u64 v[172:173], s[34:35], 0, v[132:133]
	s_mov_b32 m0, s44
	s_nop 0
	global_load_lds_dwordx4 v[172:173], off
	s_setprio 0
	s_waitcnt vmcnt(8) lgkmcnt(0)
	s_barrier
	s_setprio 1
	v_mfma_f32_16x16x32_bf16 v[126:129], v[144:147], v[206:209], v[126:129]
	v_mfma_f32_16x16x32_bf16 v[122:125], v[168:171], v[206:209], v[122:125]
	v_mfma_f32_16x16x32_bf16 v[110:113], v[144:147], v[214:217], v[110:113]
	v_mfma_f32_16x16x32_bf16 v[106:109], v[168:171], v[214:217], v[106:109]
	v_mfma_f32_16x16x32_bf16 v[92:95], v[144:147], v[222:225], v[92:95]
	v_mfma_f32_16x16x32_bf16 v[88:91], v[168:171], v[222:225], v[88:91]
	v_mfma_f32_16x16x32_bf16 v[76:79], v[144:147], v[230:233], v[76:79]
	v_mfma_f32_16x16x32_bf16 v[72:75], v[168:171], v[230:233], v[72:75]
	v_mfma_f32_16x16x32_bf16 v[126:129], v[164:167], v[210:213], v[126:129]
	v_mfma_f32_16x16x32_bf16 v[122:125], v[186:189], v[210:213], v[122:125]
	v_mfma_f32_16x16x32_bf16 v[110:113], v[164:167], v[218:221], v[110:113]
	v_mfma_f32_16x16x32_bf16 v[106:109], v[186:189], v[218:221], v[106:109]
	v_mfma_f32_16x16x32_bf16 v[92:95], v[164:167], v[226:229], v[92:95]
	v_mfma_f32_16x16x32_bf16 v[88:91], v[186:189], v[226:229], v[88:91]
	v_mfma_f32_16x16x32_bf16 v[76:79], v[164:167], v[242:245], v[76:79]
	v_mfma_f32_16x16x32_bf16 v[72:75], v[186:189], v[242:245], v[72:75]
	s_setprio 0
	s_setprio 1
	v_mfma_f32_16x16x32_bf16 v[118:121], v[190:193], v[206:209], v[118:121]
	v_mfma_f32_16x16x32_bf16 v[114:117], v[198:201], v[206:209], v[114:117]
	v_mfma_f32_16x16x32_bf16 v[102:105], v[190:193], v[214:217], v[102:105]
	v_mfma_f32_16x16x32_bf16 v[98:101], v[198:201], v[214:217], v[98:101]
	v_mfma_f32_16x16x32_bf16 v[84:87], v[190:193], v[222:225], v[84:87]
	v_mfma_f32_16x16x32_bf16 v[80:83], v[198:201], v[222:225], v[80:83]
	v_mfma_f32_16x16x32_bf16 v[68:71], v[190:193], v[230:233], v[68:71]
	v_mfma_f32_16x16x32_bf16 v[64:67], v[198:201], v[230:233], v[64:67]
	v_mfma_f32_16x16x32_bf16 v[118:121], v[194:197], v[210:213], v[118:121]
	v_mfma_f32_16x16x32_bf16 v[114:117], v[202:205], v[210:213], v[114:117]
	v_mfma_f32_16x16x32_bf16 v[102:105], v[194:197], v[218:221], v[102:105]
	v_mfma_f32_16x16x32_bf16 v[98:101], v[202:205], v[218:221], v[98:101]
	v_mfma_f32_16x16x32_bf16 v[84:87], v[194:197], v[226:229], v[84:87]
	v_mfma_f32_16x16x32_bf16 v[80:83], v[202:205], v[226:229], v[80:83]
	v_mfma_f32_16x16x32_bf16 v[68:71], v[194:197], v[242:245], v[68:71]
	v_mfma_f32_16x16x32_bf16 v[64:67], v[202:205], v[242:245], v[64:67]
	s_setprio 0
	s_barrier
	s_setprio 2
	s_add_i32 s34, s60, s40
	v_lshl_add_u64 v[148:149], v[148:149], 0, s[16:17]
	s_mov_b32 m0, s34
	ds_read_b128 v[206:209], v163 offset:49152
	ds_read_b128 v[210:213], v163 offset:50176
	ds_read_b128 v[214:217], v163 offset:51200
	ds_read_b128 v[218:221], v163 offset:52224
	ds_read_b128 v[222:225], v163 offset:53248
	ds_read_b128 v[226:229], v163 offset:54272
	ds_read_b128 v[230:233], v163 offset:55296
	ds_read_b128 v[242:245], v163 offset:56320
	global_load_lds_dwordx4 v[148:149], off
	s_add_i32 m0, s34, 0x2000
	s_add_u32 s30, s30, 0x40080
	v_lshl_add_u64 v[148:149], v[154:155], 0, s[16:17]
	s_addc_u32 s31, s31, 0
	s_add_i32 s34, s61, s40
	global_load_lds_dwordx4 v[148:149], off
	v_lshl_add_u64 v[148:149], s[30:31], 0, v[134:135]
	s_mov_b32 m0, s34
	s_nop 0
	global_load_lds_dwordx4 v[148:149], off
	v_lshl_add_u64 v[148:149], s[30:31], 0, v[130:131]
	s_add_i32 m0, s34, 0x2000
	s_nop 0
	global_load_lds_dwordx4 v[148:149], off
	v_lshl_add_u64 v[148:149], v[156:157], 0, s[16:17]
	s_mov_b32 m0, s49
	s_nop 0
	global_load_lds_dwordx4 v[148:149], off
	v_lshl_add_u64 v[148:149], v[158:159], 0, s[16:17]
	s_mov_b32 m0, s50
	s_nop 0
	global_load_lds_dwordx4 v[148:149], off
	s_setprio 0
	s_waitcnt vmcnt(8) lgkmcnt(0)
	s_barrier
	s_setprio 1
	v_mfma_f32_16x16x32_bf16 v[60:63], v[144:147], v[206:209], v[60:63]
	v_mfma_f32_16x16x32_bf16 v[56:59], v[168:171], v[206:209], v[56:59]
	v_mfma_f32_16x16x32_bf16 v[44:47], v[144:147], v[214:217], v[44:47]
	v_mfma_f32_16x16x32_bf16 v[40:43], v[168:171], v[214:217], v[40:43]
	v_mfma_f32_16x16x32_bf16 v[28:31], v[144:147], v[222:225], v[28:31]
	v_mfma_f32_16x16x32_bf16 v[24:27], v[168:171], v[222:225], v[24:27]
	v_mfma_f32_16x16x32_bf16 v[12:15], v[144:147], v[230:233], v[12:15]
	v_mfma_f32_16x16x32_bf16 v[8:11], v[168:171], v[230:233], v[8:11]
	v_mfma_f32_16x16x32_bf16 v[60:63], v[164:167], v[210:213], v[60:63]
	v_mfma_f32_16x16x32_bf16 v[56:59], v[186:189], v[210:213], v[56:59]
	v_mfma_f32_16x16x32_bf16 v[44:47], v[164:167], v[218:221], v[44:47]
	v_mfma_f32_16x16x32_bf16 v[40:43], v[186:189], v[218:221], v[40:43]
	v_mfma_f32_16x16x32_bf16 v[28:31], v[164:167], v[226:229], v[28:31]
	v_mfma_f32_16x16x32_bf16 v[24:27], v[186:189], v[226:229], v[24:27]
	v_mfma_f32_16x16x32_bf16 v[12:15], v[164:167], v[242:245], v[12:15]
	v_mfma_f32_16x16x32_bf16 v[8:11], v[186:189], v[242:245], v[8:11]
	s_setprio 0
	s_setprio 1
	v_mfma_f32_16x16x32_bf16 v[52:55], v[190:193], v[206:209], v[52:55]
	v_mfma_f32_16x16x32_bf16 v[48:51], v[198:201], v[206:209], v[48:51]
	v_mfma_f32_16x16x32_bf16 v[36:39], v[190:193], v[214:217], v[36:39]
	v_mfma_f32_16x16x32_bf16 v[32:35], v[198:201], v[214:217], v[32:35]
	v_mfma_f32_16x16x32_bf16 v[20:23], v[190:193], v[222:225], v[20:23]
	v_mfma_f32_16x16x32_bf16 v[16:19], v[198:201], v[222:225], v[16:19]
	v_mfma_f32_16x16x32_bf16 v[4:7], v[190:193], v[230:233], v[4:7]
	v_mfma_f32_16x16x32_bf16 v[0:3], v[198:201], v[230:233], v[0:3]
	v_mfma_f32_16x16x32_bf16 v[52:55], v[194:197], v[210:213], v[52:55]
	v_mfma_f32_16x16x32_bf16 v[48:51], v[202:205], v[210:213], v[48:51]
	v_mfma_f32_16x16x32_bf16 v[36:39], v[194:197], v[218:221], v[36:39]
	v_mfma_f32_16x16x32_bf16 v[32:35], v[202:205], v[218:221], v[32:35]
	v_mfma_f32_16x16x32_bf16 v[20:23], v[194:197], v[226:229], v[20:23]
	v_mfma_f32_16x16x32_bf16 v[16:19], v[202:205], v[226:229], v[16:19]
	v_mfma_f32_16x16x32_bf16 v[4:7], v[194:197], v[242:245], v[4:7]
	v_mfma_f32_16x16x32_bf16 v[0:3], v[202:205], v[242:245], v[0:3]
	s_setprio 0
	s_barrier
	s_setprio 2
	s_add_i32 s59, s59, 2
	s_add_u32 s14, s14, 0x100
	s_addc_u32 s15, s15, 0
	s_add_u32 s57, s57, 0x100
	s_addc_u32 s58, s58, 0
	s_cmp_gt_u32 s59, 13
	s_cbranch_scc0 .LBB0_449
	s_and_b64 vcc, exec, s[18:19]
	s_cbranch_vccz .LBB0_454
	s_barrier
	v_lshl_add_u32 v146, s54, 8, v150
	s_cmp_gt_i32 s53, 7
	s_mov_b64 s[14:15], -1
	s_cbranch_scc1 .LBB0_455

.LBB0_490:
	s_add_i32 s66, s6, 2
	s_add_u32 s67, s4, 0x80
	s_addc_u32 s7, s5, 0
	s_add_i32 s70, 0, 0x10000
	s_cmp_eq_u32 s60, s6
	s_cselect_b32 s7, s43, s7
	s_cselect_b32 s6, s42, s67
	v_add_u32_e32 v148, s70, v151
	s_cselect_b32 s69, s45, s15
	s_cselect_b32 s68, s44, s14
	s_add_i32 s67, 0, 0x14000
	ds_read_b128 v[140:143], v148
	ds_read_b128 v[144:147], v148 offset:1024
	ds_read_b128 v[162:165], v148 offset:2048
	ds_read_b128 v[166:169], v148 offset:3072
	v_add_u32_e32 v148, s67, v151
	ds_read_b128 v[170:173], v148
	ds_read_b128 v[186:189], v148 offset:1024
	ds_read_b128 v[190:193], v148 offset:2048
	ds_read_b128 v[194:197], v148 offset:3072
	v_lshl_add_u64 v[148:149], s[4:5], 0, v[136:137]
	s_add_i32 m0, s52, 0xc000
	ds_read_b128 v[198:201], v153
	ds_read_b128 v[202:205], v153 offset:1024
	ds_read_b128 v[206:209], v153 offset:2048
	ds_read_b128 v[210:213], v153 offset:3072
	ds_read_b128 v[214:217], v153 offset:4096
	ds_read_b128 v[218:221], v153 offset:5120
	ds_read_b128 v[222:225], v153 offset:6144
	ds_read_b128 v[226:229], v153 offset:7168
	global_load_lds_dwordx4 v[148:149], off
	v_lshl_add_u64 v[148:149], s[4:5], 0, v[138:139]
	s_add_i32 m0, s52, 0xe000
	s_nop 0
	global_load_lds_dwordx4 v[148:149], off
	s_setprio 0
	s_waitcnt vmcnt(8) lgkmcnt(0)
	s_barrier
	s_setprio 1
	v_mfma_f32_16x16x32_bf16 v[126:129], v[140:143], v[198:201], v[126:129]
	v_mfma_f32_16x16x32_bf16 v[122:125], v[162:165], v[198:201], v[122:125]
	v_mfma_f32_16x16x32_bf16 v[110:113], v[140:143], v[206:209], v[110:113]
	v_mfma_f32_16x16x32_bf16 v[106:109], v[162:165], v[206:209], v[106:109]
	v_mfma_f32_16x16x32_bf16 v[92:95], v[140:143], v[214:217], v[92:95]
	v_mfma_f32_16x16x32_bf16 v[88:91], v[162:165], v[214:217], v[88:91]
	v_mfma_f32_16x16x32_bf16 v[76:79], v[140:143], v[222:225], v[76:79]
	v_mfma_f32_16x16x32_bf16 v[72:75], v[162:165], v[222:225], v[72:75]
	v_mfma_f32_16x16x32_bf16 v[126:129], v[144:147], v[202:205], v[126:129]
	v_mfma_f32_16x16x32_bf16 v[122:125], v[166:169], v[202:205], v[122:125]
	v_mfma_f32_16x16x32_bf16 v[110:113], v[144:147], v[210:213], v[110:113]
	v_mfma_f32_16x16x32_bf16 v[106:109], v[166:169], v[210:213], v[106:109]
	v_mfma_f32_16x16x32_bf16 v[92:95], v[144:147], v[218:221], v[92:95]
	v_mfma_f32_16x16x32_bf16 v[88:91], v[166:169], v[218:221], v[88:91]
	v_mfma_f32_16x16x32_bf16 v[76:79], v[144:147], v[226:229], v[76:79]
	v_mfma_f32_16x16x32_bf16 v[72:75], v[166:169], v[226:229], v[72:75]
	s_setprio 0
	s_setprio 1
	v_mfma_f32_16x16x32_bf16 v[118:121], v[170:173], v[198:201], v[118:121]
	v_mfma_f32_16x16x32_bf16 v[114:117], v[190:193], v[198:201], v[114:117]
	v_mfma_f32_16x16x32_bf16 v[102:105], v[170:173], v[206:209], v[102:105]
	v_mfma_f32_16x16x32_bf16 v[98:101], v[190:193], v[206:209], v[98:101]
	v_mfma_f32_16x16x32_bf16 v[84:87], v[170:173], v[214:217], v[84:87]
	v_mfma_f32_16x16x32_bf16 v[80:83], v[190:193], v[214:217], v[80:83]
	v_mfma_f32_16x16x32_bf16 v[68:71], v[170:173], v[222:225], v[68:71]
	v_mfma_f32_16x16x32_bf16 v[64:67], v[190:193], v[222:225], v[64:67]
	v_mfma_f32_16x16x32_bf16 v[118:121], v[186:189], v[202:205], v[118:121]
	v_mfma_f32_16x16x32_bf16 v[114:117], v[194:197], v[202:205], v[114:117]
	v_mfma_f32_16x16x32_bf16 v[102:105], v[186:189], v[210:213], v[102:105]
	v_mfma_f32_16x16x32_bf16 v[98:101], v[194:197], v[210:213], v[98:101]
	v_mfma_f32_16x16x32_bf16 v[84:87], v[186:189], v[218:221], v[84:87]
	v_mfma_f32_16x16x32_bf16 v[80:83], v[194:197], v[218:221], v[80:83]
	v_mfma_f32_16x16x32_bf16 v[68:71], v[186:189], v[226:229], v[68:71]
	v_mfma_f32_16x16x32_bf16 v[64:67], v[194:197], v[226:229], v[64:67]
	s_setprio 0
	s_barrier
	s_setprio 2
	s_add_i32 s70, s70, s51
	v_lshl_add_u64 v[148:149], s[68:69], 0, v[96:97]
	s_mov_b32 m0, s70
	ds_read_b128 v[198:201], v153 offset:16384
	ds_read_b128 v[202:205], v153 offset:17408
	ds_read_b128 v[206:209], v153 offset:18432
	ds_read_b128 v[210:213], v153 offset:19456
	ds_read_b128 v[214:217], v153 offset:20480
	ds_read_b128 v[218:221], v153 offset:21504
	ds_read_b128 v[222:225], v153 offset:22528
	ds_read_b128 v[226:229], v153 offset:23552
	global_load_lds_dwordx4 v[148:149], off
	s_add_i32 m0, s70, 0x2000
	v_lshl_add_u64 v[154:155], s[68:69], 0, v[130:131]
	s_add_u32 s68, s68, s46
	s_addc_u32 s69, s69, 0
	s_add_i32 s67, s67, s51
	global_load_lds_dwordx4 v[154:155], off
	v_lshl_add_u64 v[156:157], s[68:69], 0, v[96:97]
	s_mov_b32 m0, s67
	v_lshl_add_u64 v[158:159], s[68:69], 0, v[130:131]
	global_load_lds_dwordx4 v[156:157], off
	s_add_i32 m0, s67, 0x2000
	v_lshl_add_u64 v[182:183], s[6:7], 0, v[134:135]
	global_load_lds_dwordx4 v[158:159], off
	s_mov_b32 m0, s52
	v_lshl_add_u64 v[184:185], s[6:7], 0, v[132:133]
	global_load_lds_dwordx4 v[182:183], off
	s_mov_b32 m0, s53
	s_nop 0
	global_load_lds_dwordx4 v[184:185], off
	s_setprio 0
	s_waitcnt vmcnt(8) lgkmcnt(0)
	s_barrier
	s_setprio 1
	v_mfma_f32_16x16x32_bf16 v[60:63], v[140:143], v[198:201], v[60:63]
	v_mfma_f32_16x16x32_bf16 v[56:59], v[162:165], v[198:201], v[56:59]
	v_mfma_f32_16x16x32_bf16 v[44:47], v[140:143], v[206:209], v[44:47]
	v_mfma_f32_16x16x32_bf16 v[40:43], v[162:165], v[206:209], v[40:43]
	v_mfma_f32_16x16x32_bf16 v[28:31], v[140:143], v[214:217], v[28:31]
	v_mfma_f32_16x16x32_bf16 v[24:27], v[162:165], v[214:217], v[24:27]
	v_mfma_f32_16x16x32_bf16 v[12:15], v[140:143], v[222:225], v[12:15]
	v_mfma_f32_16x16x32_bf16 v[8:11], v[162:165], v[222:225], v[8:11]
	v_mfma_f32_16x16x32_bf16 v[60:63], v[144:147], v[202:205], v[60:63]
	v_mfma_f32_16x16x32_bf16 v[56:59], v[166:169], v[202:205], v[56:59]
	v_mfma_f32_16x16x32_bf16 v[44:47], v[144:147], v[210:213], v[44:47]
	v_mfma_f32_16x16x32_bf16 v[40:43], v[166:169], v[210:213], v[40:43]
	v_mfma_f32_16x16x32_bf16 v[28:31], v[144:147], v[218:221], v[28:31]
	v_mfma_f32_16x16x32_bf16 v[24:27], v[166:169], v[218:221], v[24:27]
	v_mfma_f32_16x16x32_bf16 v[12:15], v[144:147], v[226:229], v[12:15]
	v_mfma_f32_16x16x32_bf16 v[8:11], v[166:169], v[226:229], v[8:11]
	s_setprio 0
	s_setprio 1
	v_mfma_f32_16x16x32_bf16 v[52:55], v[170:173], v[198:201], v[52:55]
	v_mfma_f32_16x16x32_bf16 v[48:51], v[190:193], v[198:201], v[48:51]
	v_mfma_f32_16x16x32_bf16 v[36:39], v[170:173], v[206:209], v[36:39]
	v_mfma_f32_16x16x32_bf16 v[32:35], v[190:193], v[206:209], v[32:35]
	v_mfma_f32_16x16x32_bf16 v[20:23], v[170:173], v[214:217], v[20:23]
	v_mfma_f32_16x16x32_bf16 v[16:19], v[190:193], v[214:217], v[16:19]
	v_mfma_f32_16x16x32_bf16 v[4:7], v[170:173], v[222:225], v[4:7]
	v_mfma_f32_16x16x32_bf16 v[0:3], v[190:193], v[222:225], v[0:3]
	v_mfma_f32_16x16x32_bf16 v[52:55], v[186:189], v[202:205], v[52:55]
	v_mfma_f32_16x16x32_bf16 v[48:51], v[194:197], v[202:205], v[48:51]
	v_mfma_f32_16x16x32_bf16 v[36:39], v[186:189], v[210:213], v[36:39]
	v_mfma_f32_16x16x32_bf16 v[32:35], v[194:197], v[210:213], v[32:35]
	v_mfma_f32_16x16x32_bf16 v[20:23], v[186:189], v[218:221], v[20:23]
	v_mfma_f32_16x16x32_bf16 v[16:19], v[194:197], v[218:221], v[16:19]
	v_mfma_f32_16x16x32_bf16 v[4:7], v[186:189], v[226:229], v[4:7]
	v_mfma_f32_16x16x32_bf16 v[0:3], v[194:197], v[226:229], v[0:3]
	s_setprio 0
	s_barrier
	s_setprio 2
	s_add_i32 s67, 0, 0x18000
	s_add_i32 s68, 0, 0x1c000
	v_add_u32_e32 v166, s67, v151
	v_add_u32_e32 v194, s68, v151
	ds_read_b128 v[140:143], v166
	ds_read_b128 v[144:147], v166 offset:1024
	ds_read_b128 v[162:165], v166 offset:2048
	ds_read_b128 v[166:169], v166 offset:3072
	ds_read_b128 v[170:173], v194
	ds_read_b128 v[186:189], v194 offset:1024
	ds_read_b128 v[190:193], v194 offset:2048
	ds_read_b128 v[194:197], v194 offset:3072
	s_add_u32 s6, s6, s46
	s_addc_u32 s7, s7, 0
	s_mov_b32 m0, s54
	v_lshl_add_u64 v[230:231], s[6:7], 0, v[134:135]
	ds_read_b128 v[198:201], v153 offset:32768
	ds_read_b128 v[202:205], v153 offset:33792
	ds_read_b128 v[206:209], v153 offset:34816
	ds_read_b128 v[210:213], v153 offset:35840
	ds_read_b128 v[214:217], v153 offset:36864
	ds_read_b128 v[218:221], v153 offset:37888
	ds_read_b128 v[222:225], v153 offset:38912
	ds_read_b128 v[226:229], v153 offset:39936
	global_load_lds_dwordx4 v[230:231], off
	v_lshl_add_u64 v[230:231], s[6:7], 0, v[132:133]
	s_mov_b32 m0, s55
	s_nop 0
	global_load_lds_dwordx4 v[230:231], off
	s_setprio 0
	s_waitcnt vmcnt(8) lgkmcnt(0)
	s_barrier
	s_setprio 1
	v_mfma_f32_16x16x32_bf16 v[126:129], v[140:143], v[198:201], v[126:129]
	v_mfma_f32_16x16x32_bf16 v[122:125], v[162:165], v[198:201], v[122:125]
	v_mfma_f32_16x16x32_bf16 v[110:113], v[140:143], v[206:209], v[110:113]
	v_mfma_f32_16x16x32_bf16 v[106:109], v[162:165], v[206:209], v[106:109]
	v_mfma_f32_16x16x32_bf16 v[92:95], v[140:143], v[214:217], v[92:95]
	v_mfma_f32_16x16x32_bf16 v[88:91], v[162:165], v[214:217], v[88:91]
	v_mfma_f32_16x16x32_bf16 v[76:79], v[140:143], v[222:225], v[76:79]
	v_mfma_f32_16x16x32_bf16 v[72:75], v[162:165], v[222:225], v[72:75]
	v_mfma_f32_16x16x32_bf16 v[126:129], v[144:147], v[202:205], v[126:129]
	v_mfma_f32_16x16x32_bf16 v[122:125], v[166:169], v[202:205], v[122:125]
	v_mfma_f32_16x16x32_bf16 v[110:113], v[144:147], v[210:213], v[110:113]
	v_mfma_f32_16x16x32_bf16 v[106:109], v[166:169], v[210:213], v[106:109]
	v_mfma_f32_16x16x32_bf16 v[92:95], v[144:147], v[218:221], v[92:95]
	v_mfma_f32_16x16x32_bf16 v[88:91], v[166:169], v[218:221], v[88:91]
	v_mfma_f32_16x16x32_bf16 v[76:79], v[144:147], v[226:229], v[76:79]
	v_mfma_f32_16x16x32_bf16 v[72:75], v[166:169], v[226:229], v[72:75]
	s_setprio 0
	s_setprio 1
	v_mfma_f32_16x16x32_bf16 v[118:121], v[170:173], v[198:201], v[118:121]
	v_mfma_f32_16x16x32_bf16 v[114:117], v[190:193], v[198:201], v[114:117]
	v_mfma_f32_16x16x32_bf16 v[102:105], v[170:173], v[206:209], v[102:105]
	v_mfma_f32_16x16x32_bf16 v[98:101], v[190:193], v[206:209], v[98:101]
	v_mfma_f32_16x16x32_bf16 v[84:87], v[170:173], v[214:217], v[84:87]
	v_mfma_f32_16x16x32_bf16 v[80:83], v[190:193], v[214:217], v[80:83]
	v_mfma_f32_16x16x32_bf16 v[68:71], v[170:173], v[222:225], v[68:71]
	v_mfma_f32_16x16x32_bf16 v[64:67], v[190:193], v[222:225], v[64:67]
	v_mfma_f32_16x16x32_bf16 v[118:121], v[186:189], v[202:205], v[118:121]
	v_mfma_f32_16x16x32_bf16 v[114:117], v[194:197], v[202:205], v[114:117]
	v_mfma_f32_16x16x32_bf16 v[102:105], v[186:189], v[210:213], v[102:105]
	v_mfma_f32_16x16x32_bf16 v[98:101], v[194:197], v[210:213], v[98:101]
	v_mfma_f32_16x16x32_bf16 v[84:87], v[186:189], v[218:221], v[84:87]
	v_mfma_f32_16x16x32_bf16 v[80:83], v[194:197], v[218:221], v[80:83]
	v_mfma_f32_16x16x32_bf16 v[68:71], v[186:189], v[226:229], v[68:71]
	v_mfma_f32_16x16x32_bf16 v[64:67], v[194:197], v[226:229], v[64:67]
	s_setprio 0
	s_barrier
	s_setprio 2
	s_add_i32 s6, s67, s51
	v_lshl_add_u64 v[148:149], v[148:149], 0, s[16:17]
	s_mov_b32 m0, s6
	ds_read_b128 v[198:201], v153 offset:49152
	ds_read_b128 v[202:205], v153 offset:50176
	ds_read_b128 v[206:209], v153 offset:51200
	ds_read_b128 v[210:213], v153 offset:52224
	ds_read_b128 v[214:217], v153 offset:53248
	ds_read_b128 v[218:221], v153 offset:54272
	ds_read_b128 v[222:225], v153 offset:55296
	ds_read_b128 v[226:229], v153 offset:56320
	global_load_lds_dwordx4 v[148:149], off
	v_lshl_add_u64 v[148:149], v[154:155], 0, s[16:17]
	s_add_i32 m0, s6, 0x2000
	s_add_i32 s6, s68, s51
	global_load_lds_dwordx4 v[148:149], off
	v_lshl_add_u64 v[148:149], v[156:157], 0, s[16:17]
	s_mov_b32 m0, s6
	s_nop 0
	global_load_lds_dwordx4 v[148:149], off
	v_lshl_add_u64 v[148:149], v[158:159], 0, s[16:17]
	s_add_i32 m0, s6, 0x2000
	s_nop 0
	global_load_lds_dwordx4 v[148:149], off
	v_lshl_add_u64 v[148:149], v[182:183], 0, s[16:17]
	s_mov_b32 m0, s56
	s_nop 0
	global_load_lds_dwordx4 v[148:149], off
	v_lshl_add_u64 v[148:149], v[184:185], 0, s[16:17]
	s_mov_b32 m0, s57
	s_nop 0
	global_load_lds_dwordx4 v[148:149], off
	s_setprio 0
	s_waitcnt vmcnt(8) lgkmcnt(0)
	s_barrier
	s_setprio 1
	v_mfma_f32_16x16x32_bf16 v[60:63], v[140:143], v[198:201], v[60:63]
	v_mfma_f32_16x16x32_bf16 v[56:59], v[162:165], v[198:201], v[56:59]
	v_mfma_f32_16x16x32_bf16 v[44:47], v[140:143], v[206:209], v[44:47]
	v_mfma_f32_16x16x32_bf16 v[40:43], v[162:165], v[206:209], v[40:43]
	v_mfma_f32_16x16x32_bf16 v[28:31], v[140:143], v[214:217], v[28:31]
	v_mfma_f32_16x16x32_bf16 v[24:27], v[162:165], v[214:217], v[24:27]
	v_mfma_f32_16x16x32_bf16 v[12:15], v[140:143], v[222:225], v[12:15]
	v_mfma_f32_16x16x32_bf16 v[8:11], v[162:165], v[222:225], v[8:11]
	v_mfma_f32_16x16x32_bf16 v[60:63], v[144:147], v[202:205], v[60:63]
	v_mfma_f32_16x16x32_bf16 v[56:59], v[166:169], v[202:205], v[56:59]
	v_mfma_f32_16x16x32_bf16 v[44:47], v[144:147], v[210:213], v[44:47]
	v_mfma_f32_16x16x32_bf16 v[40:43], v[166:169], v[210:213], v[40:43]
	v_mfma_f32_16x16x32_bf16 v[28:31], v[144:147], v[218:221], v[28:31]
	v_mfma_f32_16x16x32_bf16 v[24:27], v[166:169], v[218:221], v[24:27]
	v_mfma_f32_16x16x32_bf16 v[12:15], v[144:147], v[226:229], v[12:15]
	v_mfma_f32_16x16x32_bf16 v[8:11], v[166:169], v[226:229], v[8:11]
	s_setprio 0
	s_setprio 1
	v_mfma_f32_16x16x32_bf16 v[52:55], v[170:173], v[198:201], v[52:55]
	v_mfma_f32_16x16x32_bf16 v[48:51], v[190:193], v[198:201], v[48:51]
	v_mfma_f32_16x16x32_bf16 v[36:39], v[170:173], v[206:209], v[36:39]
	v_mfma_f32_16x16x32_bf16 v[32:35], v[190:193], v[206:209], v[32:35]
	v_mfma_f32_16x16x32_bf16 v[20:23], v[170:173], v[214:217], v[20:23]
	v_mfma_f32_16x16x32_bf16 v[16:19], v[190:193], v[214:217], v[16:19]
	v_mfma_f32_16x16x32_bf16 v[4:7], v[170:173], v[222:225], v[4:7]
	v_mfma_f32_16x16x32_bf16 v[0:3], v[190:193], v[222:225], v[0:3]
	v_mfma_f32_16x16x32_bf16 v[52:55], v[186:189], v[202:205], v[52:55]
	v_mfma_f32_16x16x32_bf16 v[48:51], v[194:197], v[202:205], v[48:51]
	v_mfma_f32_16x16x32_bf16 v[36:39], v[186:189], v[210:213], v[36:39]
	v_mfma_f32_16x16x32_bf16 v[32:35], v[194:197], v[210:213], v[32:35]
	v_mfma_f32_16x16x32_bf16 v[20:23], v[186:189], v[218:221], v[20:23]
	v_mfma_f32_16x16x32_bf16 v[16:19], v[194:197], v[218:221], v[16:19]
	v_mfma_f32_16x16x32_bf16 v[4:7], v[186:189], v[226:229], v[4:7]
	v_mfma_f32_16x16x32_bf16 v[0:3], v[194:197], v[226:229], v[0:3]
	s_setprio 0
	s_barrier
	s_setprio 2
	s_add_u32 s4, s4, 0x100
	s_addc_u32 s5, s5, 0
	s_add_u32 s14, s14, 0x100
	s_addc_u32 s15, s15, 0
	s_cmp_ge_u32 s66, s59
	s_mov_b32 s6, s66
	s_cbranch_scc0 .LBB0_490
	s_and_b64 vcc, exec, s[36:37]
	s_cbranch_vccz .LBB0_493
	s_barrier
